# residual-update GEMM epilogues (8 phases): 16 old-x loads per unit hoisted to epilogue start, counted waits
# baseline (speedup 1.0000x reference)
; #define EPI_LOAD_X8(d0, d1, o) do { const u32x4 h_ = *(const u32x4*)(XBo + (o)); \
;         d0[0] = BFLO(h_.x); d0[1] = BFHI(h_.x); d0[2] = BFLO(h_.y); d0[3] = BFHI(h_.y); d1[0] = BFLO(h_.z); d1[1] = BFHI(h_.z); d1[2] = BFLO(h_.w); d1[3] = BFHI(h_.w); } while (0)
;     __device__ __forceinline__ void operator()(const f32x4 (&acc)[2][2][4][2], const Unit& u, int wr, int wc, int fr, int fq) const {
;         const int row0 = u.pm * BM + wr * 64 + fr, col0 = u.pn * BM + wc * 32 + 8 * fq;
; #pragma unroll
;         for (int ai = 0; ai < 2; ++ai)
; #pragma unroll
;             for (int m = 0; m < 4; ++m) { const int r = row0 + ai * HALF + m * 16; const size_t off = (size_t)r * DM + col0; float ss = 0.f;
; #pragma unroll
;                 for (int bj = 0; bj < 2; ++bj) { const size_t o = off + bj * HALF;
;                     f32x4 v0, v1; if (F32BASE) { v0 = *(const f32x4*)(base + o); v1 = *(const f32x4*)(base + o + 4); } else EPI_LOAD_X8(v0, v1, o);
;                     v0 = v0 + acc[ai][bj][m][0]; v1 = v1 + acc[ai][bj][m][1]; EPI_STORE_X8(v0, v1, o); }
;                 ss += __shfl_xor(ss, 16); ss += __shfl_xor(ss, 32);
;                 if (fq == 0) SSQ[(size_t)r * NPART + u.pn * 4 + wc] = ss;
;                 if (m == 3) asm volatile("" ::: "memory"); }
.LBB0_567:
	s_lshl_b32 s0, s53, 8
	s_add_i32 s0, s0, s41
	v_mbcnt_lo_u32_b32 v160, -1, 0
	v_mbcnt_hi_u32_b32 v160, -1, v160
	v_xor_b32_e32 v161, 32, v145
	v_and_or_b32 v134, v160, 15, s0
	s_lshl_b32 s0, s16, 8
	v_ashrrev_i32_e32 v132, 1, v160
	s_or_b32 s0, s0, s42
	v_and_b32_e32 v132, -8, v132
	v_add_u32_e32 v132, s0, v132
	v_ashrrev_i32_e32 v135, 31, v134
	v_ashrrev_i32_e32 v133, 31, v132
	v_lshlrev_b64 v[146:147], 11, v[134:135]
	v_lshl_add_u64 v[146:147], v[146:147], 0, v[132:133]
	v_lshlrev_b64 v[150:151], 1, v[146:147]
	v_lshl_add_u64 v[152:153], s[18:19], 0, v[150:151]
	global_load_dwordx4 v[164:167], v150, s[18:19]
	global_load_dwordx4 v[168:171], v150, s[18:19] offset:256
	s_add_u32 vcc_lo, s18, 0x10000
	s_addc_u32 vcc_hi, s19, 0
	global_load_dwordx4 v[172:175], v150, vcc
	global_load_dwordx4 v[176:179], v150, vcc offset:256
	s_add_u32 s0, s18, 0x20000
	s_addc_u32 s1, s19, 0
	global_load_dwordx4 v[180:183], v150, s[0:1]
	global_load_dwordx4 v[184:187], v150, s[0:1] offset:256
	s_add_u32 vcc_lo, s18, 0x30000
	s_addc_u32 vcc_hi, s19, 0
	global_load_dwordx4 v[188:191], v150, vcc
	global_load_dwordx4 v[192:195], v150, vcc offset:256
	s_add_u32 s0, s18, 0x80000
	s_addc_u32 s1, s19, 0
	global_load_dwordx4 v[196:199], v150, s[0:1]
	global_load_dwordx4 v[200:203], v150, s[0:1] offset:256
	s_add_u32 vcc_lo, s18, 0x90000
	s_addc_u32 vcc_hi, s19, 0
	global_load_dwordx4 v[204:207], v150, vcc
	global_load_dwordx4 v[208:211], v150, vcc offset:256
	s_add_u32 s0, s18, 0xa0000
	s_addc_u32 s1, s19, 0
	global_load_dwordx4 v[212:215], v150, s[0:1]
	global_load_dwordx4 v[216:219], v150, s[0:1] offset:256
	s_add_u32 vcc_lo, s18, 0xb0000
	s_addc_u32 vcc_hi, s19, 0
	global_load_dwordx4 v[220:223], v150, vcc
	global_load_dwordx4 v[224:227], v150, vcc offset:256
	s_lshl_b32 s14, s16, 2
	v_cmp_gt_u32_e32 vcc, 16, v160
	s_ashr_i32 s15, s14, 31
	s_waitcnt vmcnt(15)
	v_mov_b32_e32 v146, v164
	v_mov_b32_e32 v147, v165
	v_mov_b32_e32 v148, v166
	v_mov_b32_e32 v149, v167
	v_lshlrev_b32_e32 v154, 16, v146
	v_and_b32_e32 v155, 0xffff0000, v146
	v_lshlrev_b32_e32 v146, 16, v147
	v_and_b32_e32 v147, 0xffff0000, v147
	v_lshlrev_b32_e32 v156, 16, v148
	v_and_b32_e32 v157, 0xffff0000, v148
	v_lshlrev_b32_e32 v148, 16, v149
	v_and_b32_e32 v149, 0xffff0000, v149
	v_pk_add_f32 v[126:127], v[126:127], v[146:147]
	v_pk_add_f32 v[154:155], v[124:125], v[154:155]
	v_pk_add_f32 v[158:159], v[122:123], v[148:149]
	v_pk_add_f32 v[156:157], v[120:121], v[156:157]
	v_cvt_pk_bf16_f32 v122, v154, v155
	v_cvt_pk_bf16_f32 v123, v126, v127
	v_mul_f32_e32 v127, v127, v127
	v_cvt_pk_bf16_f32 v124, v156, v157
	v_cvt_pk_bf16_f32 v125, v158, v159
	v_mul_f32_e32 v152, v155, v155
	v_mul_f32_e32 v153, v157, v157
	v_mul_f32_e32 v155, v159, v159
	v_fmac_f32_e32 v152, v154, v154
	v_fmac_f32_e32 v127, v126, v126
	v_fmac_f32_e32 v153, v156, v156
	v_fmac_f32_e32 v155, v158, v158
	v_add_f32_e32 v126, v152, v127
	v_add_f32_e32 v127, v153, v155
	v_add_f32_e32 v154, v126, v127
	v_and_b32_e32 v121, 64, v145
	v_xor_b32_e32 v120, 16, v145
	v_add_u32_e32 v121, 64, v121
	v_cmp_lt_i32_e64 s[0:1], v120, v121
	s_waitcnt vmcnt(14)
	v_mov_b32_e32 v146, v168
	v_mov_b32_e32 v147, v169
	v_mov_b32_e32 v148, v170
	v_mov_b32_e32 v149, v171
	v_lshlrev_b32_e32 v126, 16, v146
	v_and_b32_e32 v127, 0xffff0000, v146
	v_lshlrev_b32_e32 v146, 16, v147
	v_and_b32_e32 v147, 0xffff0000, v147
	v_lshlrev_b32_e32 v152, 16, v148
	v_and_b32_e32 v153, 0xffff0000, v148
	v_lshlrev_b32_e32 v148, 16, v149
	v_and_b32_e32 v149, 0xffff0000, v149
	v_pk_add_f32 v[118:119], v[118:119], v[146:147]
	v_pk_add_f32 v[116:117], v[116:117], v[126:127]
	v_pk_add_f32 v[126:127], v[114:115], v[148:149]
	v_pk_add_f32 v[146:147], v[112:113], v[152:153]
	v_mul_f32_e32 v112, v117, v117
	v_mul_f32_e32 v113, v119, v119
	v_mul_f32_e32 v114, v147, v147
	v_mul_f32_e32 v115, v127, v127
	v_fmac_f32_e32 v112, v116, v116
	v_fmac_f32_e32 v113, v118, v118
	v_fmac_f32_e32 v114, v146, v146
	v_fmac_f32_e32 v115, v126, v126
	v_add_f32_e32 v112, v112, v113
	v_add_f32_e32 v113, v114, v115
	v_cndmask_b32_e64 v120, v145, v120, s[0:1]
	v_add_f32_e32 v112, v112, v113
	v_lshlrev_b32_e32 v120, 2, v120
	v_add_f32_e32 v112, v154, v112
	ds_bpermute_b32 v113, v120, v112
	v_cmp_lt_i32_e64 s[0:1], v161, v121
	v_lshl_add_u64 v[148:149], s[20:21], 0, v[150:151]
	global_store_dwordx4 v[148:149], v[122:125], off
	v_cndmask_b32_e64 v114, v145, v161, s[0:1]
	s_waitcnt lgkmcnt(0)
	v_add_f32_e32 v112, v112, v113
	v_lshlrev_b32_e32 v114, 2, v114
	ds_bpermute_b32 v113, v114, v112
	v_cvt_pk_bf16_f32 v116, v116, v117
	v_cvt_pk_bf16_f32 v117, v118, v119
	v_cvt_pk_bf16_f32 v118, v146, v147
	v_cvt_pk_bf16_f32 v119, v126, v127
	global_store_dwordx4 v[148:149], v[116:119], off offset:256
	s_and_saveexec_b64 s[0:1], vcc
	s_cbranch_execz .LBB0_569
	s_waitcnt lgkmcnt(0)
	v_add_f32_e32 v115, v112, v113
	v_lshlrev_b64 v[112:113], 7, v[134:135]
	v_lshl_add_u64 v[112:113], s[22:23], 0, v[112:113]
	v_lshl_add_u64 v[112:113], s[14:15], 2, v[112:113]
	s_lshl_b32 s16, s40, 2
	v_lshl_add_u64 v[112:113], v[112:113], 0, s[16:17]
	global_store_dword v[112:113], v115, off
; #define EPI_LOAD_X8(d0, d1, o) do { const u32x4 h_ = *(const u32x4*)(XBo + (o)); \
;         d0[0] = BFLO(h_.x); d0[1] = BFHI(h_.x); d0[2] = BFLO(h_.y); d0[3] = BFHI(h_.y); d1[0] = BFLO(h_.z); d1[1] = BFHI(h_.z); d1[2] = BFLO(h_.w); d1[3] = BFHI(h_.w); } while (0)
;     __device__ __forceinline__ void operator()(const f32x4 (&acc)[2][2][4][2], const Unit& u, int wr, int wc, int fr, int fq) const {
;     ...
;             for (int m = 0; m < 4; ++m) { const int r = row0 + ai * HALF + m * 16; const size_t off = (size_t)r * DM + col0; float ss = 0.f;
; #pragma unroll
;                 for (int bj = 0; bj < 2; ++bj) { const size_t o = off + bj * HALF;
;                     f32x4 v0, v1; if (F32BASE) { v0 = *(const f32x4*)(base + o); v1 = *(const f32x4*)(base + o + 4); } else EPI_LOAD_X8(v0, v1, o);
;                     v0 = v0 + acc[ai][bj][m][0]; v1 = v1 + acc[ai][bj][m][1]; EPI_STORE_X8(v0, v1, o); }
;                 ss += __shfl_xor(ss, 16); ss += __shfl_xor(ss, 32);
;                 if (fq == 0) SSQ[(size_t)r * NPART + u.pn * 4 + wc] = ss;
;                 if (m == 3) asm volatile("" ::: "memory"); }
.LBB0_569:
	s_or_b64 exec, exec, s[0:1]
	v_or_b32_e32 v112, 16, v134
	s_waitcnt lgkmcnt(0)
	v_ashrrev_i32_e32 v113, 31, v112
	v_lshlrev_b64 v[116:117], 11, v[112:113]
	v_lshl_add_u64 v[116:117], v[116:117], 0, v[132:133]
	v_lshlrev_b64 v[122:123], 1, v[116:117]
	v_lshl_add_u64 v[124:125], s[18:19], 0, v[122:123]
	s_waitcnt vmcnt(16)
	v_mov_b32_e32 v116, v172
	v_mov_b32_e32 v117, v173
	v_mov_b32_e32 v118, v174
	v_mov_b32_e32 v119, v175
	v_lshlrev_b32_e32 v126, 16, v116
	v_and_b32_e32 v127, 0xffff0000, v116
	v_lshlrev_b32_e32 v116, 16, v117
	v_and_b32_e32 v117, 0xffff0000, v117
	v_lshlrev_b32_e32 v146, 16, v118
	v_and_b32_e32 v147, 0xffff0000, v118
	v_lshlrev_b32_e32 v118, 16, v119
	v_and_b32_e32 v119, 0xffff0000, v119
	v_pk_add_f32 v[116:117], v[110:111], v[116:117]
	v_pk_add_f32 v[126:127], v[108:109], v[126:127]
	v_pk_add_f32 v[118:119], v[106:107], v[118:119]
	v_pk_add_f32 v[146:147], v[104:105], v[146:147]
	v_cvt_pk_bf16_f32 v104, v126, v127
	v_cvt_pk_bf16_f32 v105, v116, v117
	v_mul_f32_e32 v115, v127, v127
	v_cvt_pk_bf16_f32 v106, v146, v147
	v_cvt_pk_bf16_f32 v107, v118, v119
	v_mul_f32_e32 v117, v117, v117
	v_mul_f32_e32 v121, v147, v147
	v_mul_f32_e32 v119, v119, v119
	v_fmac_f32_e32 v115, v126, v126
	v_fmac_f32_e32 v117, v116, v116
	v_fmac_f32_e32 v121, v146, v146
	v_fmac_f32_e32 v119, v118, v118
	v_add_f32_e32 v115, v115, v117
	v_add_f32_e32 v116, v121, v119
	v_add_f32_e32 v115, v115, v116
	s_waitcnt vmcnt(15)
	v_mov_b32_e32 v108, v176
	v_mov_b32_e32 v109, v177
	v_mov_b32_e32 v110, v178
	v_mov_b32_e32 v111, v179
	v_lshlrev_b32_e32 v116, 16, v108
	v_and_b32_e32 v117, 0xffff0000, v108
	v_lshlrev_b32_e32 v108, 16, v109
	v_and_b32_e32 v109, 0xffff0000, v109
	v_lshlrev_b32_e32 v118, 16, v110
	v_and_b32_e32 v119, 0xffff0000, v110
	v_lshlrev_b32_e32 v110, 16, v111
	v_and_b32_e32 v111, 0xffff0000, v111
	v_pk_add_f32 v[102:103], v[102:103], v[108:109]
	v_pk_add_f32 v[100:101], v[100:101], v[116:117]
	v_pk_add_f32 v[108:109], v[98:99], v[110:111]
	v_pk_add_f32 v[110:111], v[96:97], v[118:119]
	v_mul_f32_e32 v96, v101, v101
	v_mul_f32_e32 v97, v103, v103
	v_mul_f32_e32 v98, v111, v111
	v_mul_f32_e32 v99, v109, v109
	v_fmac_f32_e32 v96, v100, v100
	v_fmac_f32_e32 v97, v102, v102
	v_fmac_f32_e32 v98, v110, v110
	v_fmac_f32_e32 v99, v108, v108
	v_add_f32_e32 v96, v96, v97
	v_add_f32_e32 v97, v98, v99
	v_add_f32_e32 v96, v96, v97
	v_add_f32_e32 v96, v115, v96
	ds_bpermute_b32 v97, v120, v96
	v_lshl_add_u64 v[116:117], s[20:21], 0, v[122:123]
	global_store_dwordx4 v[116:117], v[104:107], off
	v_cvt_pk_bf16_f32 v98, v100, v101
	v_cvt_pk_bf16_f32 v99, v102, v103
	s_waitcnt lgkmcnt(0)
	v_add_f32_e32 v96, v96, v97
	ds_bpermute_b32 v97, v114, v96
	v_cvt_pk_bf16_f32 v100, v110, v111
	v_cvt_pk_bf16_f32 v101, v108, v109
	global_store_dwordx4 v[116:117], v[98:101], off offset:256
	s_and_saveexec_b64 s[0:1], vcc
	s_cbranch_execz .LBB0_571
	s_waitcnt lgkmcnt(0)
	v_add_f32_e32 v98, v96, v97
	v_lshlrev_b64 v[96:97], 7, v[112:113]
	v_lshl_add_u64 v[96:97], s[22:23], 0, v[96:97]
	v_lshl_add_u64 v[96:97], s[14:15], 2, v[96:97]
	s_lshl_b32 s16, s40, 2
	v_lshl_add_u64 v[96:97], v[96:97], 0, s[16:17]
	global_store_dword v[96:97], v98, off
.LBB0_571:
	s_or_b64 exec, exec, s[0:1]
	v_or_b32_e32 v96, 32, v134
	s_waitcnt lgkmcnt(0)
	v_ashrrev_i32_e32 v97, 31, v96
	v_lshlrev_b64 v[98:99], 11, v[96:97]
	v_lshl_add_u64 v[98:99], v[98:99], 0, v[132:133]
	v_lshlrev_b64 v[102:103], 1, v[98:99]
	v_lshl_add_u64 v[104:105], s[18:19], 0, v[102:103]
	s_waitcnt vmcnt(17)
	v_mov_b32_e32 v98, v180
	v_mov_b32_e32 v99, v181
	v_mov_b32_e32 v100, v182
	v_mov_b32_e32 v101, v183
	v_lshlrev_b32_e32 v106, 16, v98
	v_and_b32_e32 v107, 0xffff0000, v98
	v_lshlrev_b32_e32 v98, 16, v99
	v_and_b32_e32 v99, 0xffff0000, v99
	v_lshlrev_b32_e32 v108, 16, v100
	v_and_b32_e32 v109, 0xffff0000, v100
	v_lshlrev_b32_e32 v100, 16, v101
	v_and_b32_e32 v101, 0xffff0000, v101
	v_pk_add_f32 v[98:99], v[94:95], v[98:99]
	v_pk_add_f32 v[106:107], v[92:93], v[106:107]
	v_pk_add_f32 v[100:101], v[90:91], v[100:101]
	v_pk_add_f32 v[108:109], v[88:89], v[108:109]
	v_cvt_pk_bf16_f32 v88, v106, v107
	v_cvt_pk_bf16_f32 v89, v98, v99
	v_mul_f32_e32 v99, v99, v99
	v_cvt_pk_bf16_f32 v90, v108, v109
	v_cvt_pk_bf16_f32 v91, v100, v101
	v_mul_f32_e32 v104, v107, v107
	v_mul_f32_e32 v105, v109, v109
	v_mul_f32_e32 v101, v101, v101
	v_fmac_f32_e32 v104, v106, v106
	v_fmac_f32_e32 v99, v98, v98
	v_fmac_f32_e32 v105, v108, v108
	v_fmac_f32_e32 v101, v100, v100
	v_add_f32_e32 v98, v104, v99
	v_add_f32_e32 v99, v105, v101
	v_add_f32_e32 v104, v98, v99
	s_waitcnt vmcnt(16)
	v_mov_b32_e32 v92, v184
	v_mov_b32_e32 v93, v185
	v_mov_b32_e32 v94, v186
	v_mov_b32_e32 v95, v187
	v_lshlrev_b32_e32 v98, 16, v92
	v_and_b32_e32 v99, 0xffff0000, v92
	v_lshlrev_b32_e32 v92, 16, v93
	v_and_b32_e32 v93, 0xffff0000, v93
	v_lshlrev_b32_e32 v100, 16, v94
	v_and_b32_e32 v101, 0xffff0000, v94
	v_lshlrev_b32_e32 v94, 16, v95
	v_and_b32_e32 v95, 0xffff0000, v95
	v_pk_add_f32 v[86:87], v[86:87], v[92:93]
	v_pk_add_f32 v[84:85], v[84:85], v[98:99]
	v_pk_add_f32 v[92:93], v[82:83], v[94:95]
	v_pk_add_f32 v[94:95], v[80:81], v[100:101]
	v_mul_f32_e32 v80, v85, v85
	v_mul_f32_e32 v81, v87, v87
	v_mul_f32_e32 v82, v95, v95
	v_mul_f32_e32 v83, v93, v93
	v_fmac_f32_e32 v80, v84, v84
	v_fmac_f32_e32 v81, v86, v86
	v_fmac_f32_e32 v82, v94, v94
	v_fmac_f32_e32 v83, v92, v92
	v_add_f32_e32 v80, v80, v81
	v_add_f32_e32 v81, v82, v83
	v_add_f32_e32 v80, v80, v81
	v_add_f32_e32 v80, v104, v80
	ds_bpermute_b32 v81, v120, v80
	v_lshl_add_u64 v[98:99], s[20:21], 0, v[102:103]
	global_store_dwordx4 v[98:99], v[88:91], off
	v_cvt_pk_bf16_f32 v82, v84, v85
	v_cvt_pk_bf16_f32 v83, v86, v87
	s_waitcnt lgkmcnt(0)
	v_add_f32_e32 v80, v80, v81
	ds_bpermute_b32 v81, v114, v80
	v_cvt_pk_bf16_f32 v84, v94, v95
	v_cvt_pk_bf16_f32 v85, v92, v93
	global_store_dwordx4 v[98:99], v[82:85], off offset:256
	s_and_saveexec_b64 s[0:1], vcc
	s_cbranch_execz .LBB0_573
	s_waitcnt lgkmcnt(0)
	v_add_f32_e32 v82, v80, v81
	v_lshlrev_b64 v[80:81], 7, v[96:97]
	v_lshl_add_u64 v[80:81], s[22:23], 0, v[80:81]
	v_lshl_add_u64 v[80:81], s[14:15], 2, v[80:81]
	s_lshl_b32 s16, s40, 2
	v_lshl_add_u64 v[80:81], v[80:81], 0, s[16:17]
	global_store_dword v[80:81], v82, off
; #define EPI_LOAD_X8(d0, d1, o) do { const u32x4 h_ = *(const u32x4*)(XBo + (o)); \
;         d0[0] = BFLO(h_.x); d0[1] = BFHI(h_.x); d0[2] = BFLO(h_.y); d0[3] = BFHI(h_.y); d1[0] = BFLO(h_.z); d1[1] = BFHI(h_.z); d1[2] = BFLO(h_.w); d1[3] = BFHI(h_.w); } while (0)
;     __device__ __forceinline__ void operator()(const f32x4 (&acc)[2][2][4][2], const Unit& u, int wr, int wc, int fr, int fq) const {
;     ...
;             for (int m = 0; m < 4; ++m) { const int r = row0 + ai * HALF + m * 16; const size_t off = (size_t)r * DM + col0; float ss = 0.f;
; #pragma unroll
;                 for (int bj = 0; bj < 2; ++bj) { const size_t o = off + bj * HALF;
;                     f32x4 v0, v1; if (F32BASE) { v0 = *(const f32x4*)(base + o); v1 = *(const f32x4*)(base + o + 4); } else EPI_LOAD_X8(v0, v1, o);
;                     v0 = v0 + acc[ai][bj][m][0]; v1 = v1 + acc[ai][bj][m][1]; EPI_STORE_X8(v0, v1, o); }
;                 ss += __shfl_xor(ss, 16); ss += __shfl_xor(ss, 32);
;                 if (fq == 0) SSQ[(size_t)r * NPART + u.pn * 4 + wc] = ss;
;                 if (m == 3) asm volatile("" ::: "memory"); }
.LBB0_573:
	s_or_b64 exec, exec, s[0:1]
	v_or_b32_e32 v80, 48, v134
	s_waitcnt lgkmcnt(0)
	v_ashrrev_i32_e32 v81, 31, v80
	v_lshlrev_b64 v[82:83], 11, v[80:81]
	v_lshl_add_u64 v[82:83], v[82:83], 0, v[132:133]
	v_lshlrev_b64 v[86:87], 1, v[82:83]
	v_lshl_add_u64 v[88:89], s[18:19], 0, v[86:87]
	s_waitcnt vmcnt(18)
	v_mov_b32_e32 v82, v188
	v_mov_b32_e32 v83, v189
	v_mov_b32_e32 v84, v190
	v_mov_b32_e32 v85, v191
	v_lshlrev_b32_e32 v90, 16, v82
	v_and_b32_e32 v91, 0xffff0000, v82
	v_lshlrev_b32_e32 v82, 16, v83
	v_and_b32_e32 v83, 0xffff0000, v83
	v_lshlrev_b32_e32 v92, 16, v84
	v_and_b32_e32 v93, 0xffff0000, v84
	v_lshlrev_b32_e32 v84, 16, v85
	v_and_b32_e32 v85, 0xffff0000, v85
	v_pk_add_f32 v[82:83], v[78:79], v[82:83]
	v_pk_add_f32 v[90:91], v[76:77], v[90:91]
	v_pk_add_f32 v[84:85], v[74:75], v[84:85]
	v_pk_add_f32 v[92:93], v[72:73], v[92:93]
	v_cvt_pk_bf16_f32 v72, v90, v91
	v_cvt_pk_bf16_f32 v73, v82, v83
	v_mul_f32_e32 v83, v83, v83
	v_cvt_pk_bf16_f32 v74, v92, v93
	v_cvt_pk_bf16_f32 v75, v84, v85
	v_mul_f32_e32 v88, v91, v91
	v_mul_f32_e32 v89, v93, v93
	v_mul_f32_e32 v85, v85, v85
	v_fmac_f32_e32 v88, v90, v90
	v_fmac_f32_e32 v83, v82, v82
	v_fmac_f32_e32 v89, v92, v92
	v_fmac_f32_e32 v85, v84, v84
	v_add_f32_e32 v82, v88, v83
	v_add_f32_e32 v83, v89, v85
	v_add_f32_e32 v88, v82, v83
	s_waitcnt vmcnt(17)
	v_mov_b32_e32 v76, v192
	v_mov_b32_e32 v77, v193
	v_mov_b32_e32 v78, v194
	v_mov_b32_e32 v79, v195
	v_lshlrev_b32_e32 v82, 16, v76
	v_and_b32_e32 v83, 0xffff0000, v76
	v_lshlrev_b32_e32 v76, 16, v77
	v_and_b32_e32 v77, 0xffff0000, v77
	v_lshlrev_b32_e32 v84, 16, v78
	v_and_b32_e32 v85, 0xffff0000, v78
	v_lshlrev_b32_e32 v78, 16, v79
	v_and_b32_e32 v79, 0xffff0000, v79
	v_pk_add_f32 v[70:71], v[70:71], v[76:77]
	v_pk_add_f32 v[68:69], v[68:69], v[82:83]
	v_pk_add_f32 v[76:77], v[66:67], v[78:79]
	v_pk_add_f32 v[78:79], v[64:65], v[84:85]
	v_mul_f32_e32 v64, v69, v69
	v_mul_f32_e32 v65, v71, v71
	v_mul_f32_e32 v66, v79, v79
	v_mul_f32_e32 v67, v77, v77
	v_fmac_f32_e32 v64, v68, v68
	v_fmac_f32_e32 v65, v70, v70
	v_fmac_f32_e32 v66, v78, v78
	v_fmac_f32_e32 v67, v76, v76
	v_add_f32_e32 v64, v64, v65
	v_add_f32_e32 v65, v66, v67
	v_add_f32_e32 v64, v64, v65
	v_add_f32_e32 v64, v88, v64
	ds_bpermute_b32 v65, v120, v64
	v_lshl_add_u64 v[82:83], s[20:21], 0, v[86:87]
	global_store_dwordx4 v[82:83], v[72:75], off
	v_cvt_pk_bf16_f32 v66, v68, v69
	v_cvt_pk_bf16_f32 v67, v70, v71
	s_waitcnt lgkmcnt(0)
	v_add_f32_e32 v64, v64, v65
	ds_bpermute_b32 v65, v114, v64
	v_cvt_pk_bf16_f32 v68, v78, v79
	v_cvt_pk_bf16_f32 v69, v76, v77
	global_store_dwordx4 v[82:83], v[66:69], off offset:256
	s_and_saveexec_b64 s[0:1], vcc
	s_cbranch_execz .LBB0_575
	s_waitcnt lgkmcnt(0)
	v_add_f32_e32 v66, v64, v65
	v_lshlrev_b64 v[64:65], 7, v[80:81]
	v_lshl_add_u64 v[64:65], s[22:23], 0, v[64:65]
	v_lshl_add_u64 v[64:65], s[14:15], 2, v[64:65]
	s_lshl_b32 s16, s40, 2
	v_lshl_add_u64 v[64:65], v[64:65], 0, s[16:17]
	global_store_dword v[64:65], v66, off
.LBB0_575:
	s_or_b64 exec, exec, s[0:1]
	v_add_u32_e32 v64, 0x80, v134
	s_waitcnt lgkmcnt(0)
	v_ashrrev_i32_e32 v65, 31, v64
	v_lshlrev_b64 v[66:67], 11, v[64:65]
	v_lshl_add_u64 v[66:67], v[66:67], 0, v[132:133]
	v_lshlrev_b64 v[70:71], 1, v[66:67]
	v_lshl_add_u64 v[72:73], s[18:19], 0, v[70:71]
	s_waitcnt vmcnt(19)
	v_mov_b32_e32 v66, v196
	v_mov_b32_e32 v67, v197
	v_mov_b32_e32 v68, v198
	v_mov_b32_e32 v69, v199
	v_lshlrev_b32_e32 v74, 16, v66
	v_and_b32_e32 v75, 0xffff0000, v66
	v_lshlrev_b32_e32 v66, 16, v67
	v_and_b32_e32 v67, 0xffff0000, v67
	v_lshlrev_b32_e32 v76, 16, v68
	v_and_b32_e32 v77, 0xffff0000, v68
	v_lshlrev_b32_e32 v68, 16, v69
	v_and_b32_e32 v69, 0xffff0000, v69
	v_pk_add_f32 v[66:67], v[62:63], v[66:67]
	v_pk_add_f32 v[74:75], v[60:61], v[74:75]
	v_pk_add_f32 v[68:69], v[58:59], v[68:69]
	v_pk_add_f32 v[76:77], v[56:57], v[76:77]
	v_cvt_pk_bf16_f32 v56, v74, v75
	v_cvt_pk_bf16_f32 v57, v66, v67
	v_mul_f32_e32 v67, v67, v67
	v_cvt_pk_bf16_f32 v58, v76, v77
	v_cvt_pk_bf16_f32 v59, v68, v69
	v_mul_f32_e32 v72, v75, v75
	v_mul_f32_e32 v73, v77, v77
	v_mul_f32_e32 v69, v69, v69
	v_fmac_f32_e32 v72, v74, v74
	v_fmac_f32_e32 v67, v66, v66
	v_fmac_f32_e32 v73, v76, v76
	v_fmac_f32_e32 v69, v68, v68
	v_add_f32_e32 v66, v72, v67
	v_add_f32_e32 v67, v73, v69
	v_add_f32_e32 v72, v66, v67
	s_waitcnt vmcnt(18)
	v_mov_b32_e32 v60, v200
	v_mov_b32_e32 v61, v201
	v_mov_b32_e32 v62, v202
	v_mov_b32_e32 v63, v203
	v_lshlrev_b32_e32 v66, 16, v60
	v_and_b32_e32 v67, 0xffff0000, v60
	v_lshlrev_b32_e32 v60, 16, v61
	v_and_b32_e32 v61, 0xffff0000, v61
	v_lshlrev_b32_e32 v68, 16, v62
	v_and_b32_e32 v69, 0xffff0000, v62
	v_lshlrev_b32_e32 v62, 16, v63
	v_and_b32_e32 v63, 0xffff0000, v63
	v_pk_add_f32 v[54:55], v[54:55], v[60:61]
	v_pk_add_f32 v[52:53], v[52:53], v[66:67]
	v_pk_add_f32 v[60:61], v[50:51], v[62:63]
	v_pk_add_f32 v[62:63], v[48:49], v[68:69]
	v_mul_f32_e32 v48, v53, v53
	v_mul_f32_e32 v49, v55, v55
	v_mul_f32_e32 v50, v63, v63
	v_mul_f32_e32 v51, v61, v61
	v_fmac_f32_e32 v48, v52, v52
	v_fmac_f32_e32 v49, v54, v54
	v_fmac_f32_e32 v50, v62, v62
	v_fmac_f32_e32 v51, v60, v60
	v_add_f32_e32 v48, v48, v49
	v_add_f32_e32 v49, v50, v51
	v_add_f32_e32 v48, v48, v49
	v_add_f32_e32 v48, v72, v48
	ds_bpermute_b32 v49, v120, v48
	v_lshl_add_u64 v[66:67], s[20:21], 0, v[70:71]
	global_store_dwordx4 v[66:67], v[56:59], off
	v_cvt_pk_bf16_f32 v50, v52, v53
	v_cvt_pk_bf16_f32 v51, v54, v55
	s_waitcnt lgkmcnt(0)
	v_add_f32_e32 v48, v48, v49
	ds_bpermute_b32 v49, v114, v48
	v_cvt_pk_bf16_f32 v52, v62, v63
	v_cvt_pk_bf16_f32 v53, v60, v61
	global_store_dwordx4 v[66:67], v[50:53], off offset:256
	s_and_saveexec_b64 s[0:1], vcc
	s_cbranch_execz .LBB0_577
	s_waitcnt lgkmcnt(0)
	v_add_f32_e32 v50, v48, v49
	v_lshlrev_b64 v[48:49], 7, v[64:65]
	v_lshl_add_u64 v[48:49], s[22:23], 0, v[48:49]
	v_lshl_add_u64 v[48:49], s[14:15], 2, v[48:49]
	s_lshl_b32 s16, s40, 2
	v_lshl_add_u64 v[48:49], v[48:49], 0, s[16:17]
	global_store_dword v[48:49], v50, off
; #define EPI_LOAD_X8(d0, d1, o) do { const u32x4 h_ = *(const u32x4*)(XBo + (o)); \
;         d0[0] = BFLO(h_.x); d0[1] = BFHI(h_.x); d0[2] = BFLO(h_.y); d0[3] = BFHI(h_.y); d1[0] = BFLO(h_.z); d1[1] = BFHI(h_.z); d1[2] = BFLO(h_.w); d1[3] = BFHI(h_.w); } while (0)
;     __device__ __forceinline__ void operator()(const f32x4 (&acc)[2][2][4][2], const Unit& u, int wr, int wc, int fr, int fq) const {
;     ...
;             for (int m = 0; m < 4; ++m) { const int r = row0 + ai * HALF + m * 16; const size_t off = (size_t)r * DM + col0; float ss = 0.f;
; #pragma unroll
;                 for (int bj = 0; bj < 2; ++bj) { const size_t o = off + bj * HALF;
;                     f32x4 v0, v1; if (F32BASE) { v0 = *(const f32x4*)(base + o); v1 = *(const f32x4*)(base + o + 4); } else EPI_LOAD_X8(v0, v1, o);
;                     v0 = v0 + acc[ai][bj][m][0]; v1 = v1 + acc[ai][bj][m][1]; EPI_STORE_X8(v0, v1, o); }
;                 ss += __shfl_xor(ss, 16); ss += __shfl_xor(ss, 32);
;                 if (fq == 0) SSQ[(size_t)r * NPART + u.pn * 4 + wc] = ss;
;                 if (m == 3) asm volatile("" ::: "memory"); }
.LBB0_577:
	s_or_b64 exec, exec, s[0:1]
	v_add_u32_e32 v48, 0x90, v134
	s_waitcnt lgkmcnt(0)
	v_ashrrev_i32_e32 v49, 31, v48
	v_lshlrev_b64 v[50:51], 11, v[48:49]
	v_lshl_add_u64 v[50:51], v[50:51], 0, v[132:133]
	v_lshlrev_b64 v[54:55], 1, v[50:51]
	v_lshl_add_u64 v[56:57], s[18:19], 0, v[54:55]
	s_waitcnt vmcnt(20)
	v_mov_b32_e32 v50, v204
	v_mov_b32_e32 v51, v205
	v_mov_b32_e32 v52, v206
	v_mov_b32_e32 v53, v207
	v_lshlrev_b32_e32 v58, 16, v50
	v_and_b32_e32 v59, 0xffff0000, v50
	v_lshlrev_b32_e32 v50, 16, v51
	v_and_b32_e32 v51, 0xffff0000, v51
	v_lshlrev_b32_e32 v60, 16, v52
	v_and_b32_e32 v61, 0xffff0000, v52
	v_lshlrev_b32_e32 v52, 16, v53
	v_and_b32_e32 v53, 0xffff0000, v53
	v_pk_add_f32 v[50:51], v[46:47], v[50:51]
	v_pk_add_f32 v[58:59], v[44:45], v[58:59]
	v_pk_add_f32 v[52:53], v[42:43], v[52:53]
	v_pk_add_f32 v[60:61], v[40:41], v[60:61]
	v_cvt_pk_bf16_f32 v40, v58, v59
	v_cvt_pk_bf16_f32 v41, v50, v51
	v_mul_f32_e32 v51, v51, v51
	v_cvt_pk_bf16_f32 v42, v60, v61
	v_cvt_pk_bf16_f32 v43, v52, v53
	v_mul_f32_e32 v56, v59, v59
	v_mul_f32_e32 v57, v61, v61
	v_mul_f32_e32 v53, v53, v53
	v_fmac_f32_e32 v56, v58, v58
	v_fmac_f32_e32 v51, v50, v50
	v_fmac_f32_e32 v57, v60, v60
	v_fmac_f32_e32 v53, v52, v52
	v_add_f32_e32 v50, v56, v51
	v_add_f32_e32 v51, v57, v53
	v_add_f32_e32 v56, v50, v51
	s_waitcnt vmcnt(19)
	v_mov_b32_e32 v44, v208
	v_mov_b32_e32 v45, v209
	v_mov_b32_e32 v46, v210
	v_mov_b32_e32 v47, v211
	v_lshlrev_b32_e32 v50, 16, v44
	v_and_b32_e32 v51, 0xffff0000, v44
	v_lshlrev_b32_e32 v44, 16, v45
	v_and_b32_e32 v45, 0xffff0000, v45
	v_lshlrev_b32_e32 v52, 16, v46
	v_and_b32_e32 v53, 0xffff0000, v46
	v_lshlrev_b32_e32 v46, 16, v47
	v_and_b32_e32 v47, 0xffff0000, v47
	v_pk_add_f32 v[38:39], v[38:39], v[44:45]
	v_pk_add_f32 v[36:37], v[36:37], v[50:51]
	v_pk_add_f32 v[44:45], v[34:35], v[46:47]
	v_pk_add_f32 v[46:47], v[32:33], v[52:53]
	v_mul_f32_e32 v32, v37, v37
	v_mul_f32_e32 v33, v39, v39
	v_mul_f32_e32 v34, v47, v47
	v_mul_f32_e32 v35, v45, v45
	v_fmac_f32_e32 v32, v36, v36
	v_fmac_f32_e32 v33, v38, v38
	v_fmac_f32_e32 v34, v46, v46
	v_fmac_f32_e32 v35, v44, v44
	v_add_f32_e32 v32, v32, v33
	v_add_f32_e32 v33, v34, v35
	v_add_f32_e32 v32, v32, v33
	v_add_f32_e32 v32, v56, v32
	ds_bpermute_b32 v33, v120, v32
	v_lshl_add_u64 v[50:51], s[20:21], 0, v[54:55]
	global_store_dwordx4 v[50:51], v[40:43], off
	v_cvt_pk_bf16_f32 v34, v36, v37
	v_cvt_pk_bf16_f32 v35, v38, v39
	s_waitcnt lgkmcnt(0)
	v_add_f32_e32 v32, v32, v33
	ds_bpermute_b32 v33, v114, v32
	v_cvt_pk_bf16_f32 v36, v46, v47
	v_cvt_pk_bf16_f32 v37, v44, v45
	global_store_dwordx4 v[50:51], v[34:37], off offset:256
	s_and_saveexec_b64 s[0:1], vcc
	s_cbranch_execz .LBB0_579
	s_waitcnt lgkmcnt(0)
	v_add_f32_e32 v34, v32, v33
	v_lshlrev_b64 v[32:33], 7, v[48:49]
	v_lshl_add_u64 v[32:33], s[22:23], 0, v[32:33]
	v_lshl_add_u64 v[32:33], s[14:15], 2, v[32:33]
	s_lshl_b32 s16, s40, 2
	v_lshl_add_u64 v[32:33], v[32:33], 0, s[16:17]
	global_store_dword v[32:33], v34, off
; #define EPI_LOAD_X8(d0, d1, o) do { const u32x4 h_ = *(const u32x4*)(XBo + (o)); \
;         d0[0] = BFLO(h_.x); d0[1] = BFHI(h_.x); d0[2] = BFLO(h_.y); d0[3] = BFHI(h_.y); d1[0] = BFLO(h_.z); d1[1] = BFHI(h_.z); d1[2] = BFLO(h_.w); d1[3] = BFHI(h_.w); } while (0)
;     __device__ __forceinline__ void operator()(const f32x4 (&acc)[2][2][4][2], const Unit& u, int wr, int wc, int fr, int fq) const {
;     ...
;             for (int m = 0; m < 4; ++m) { const int r = row0 + ai * HALF + m * 16; const size_t off = (size_t)r * DM + col0; float ss = 0.f;
; #pragma unroll
;                 for (int bj = 0; bj < 2; ++bj) { const size_t o = off + bj * HALF;
;                     f32x4 v0, v1; if (F32BASE) { v0 = *(const f32x4*)(base + o); v1 = *(const f32x4*)(base + o + 4); } else EPI_LOAD_X8(v0, v1, o);
;                     v0 = v0 + acc[ai][bj][m][0]; v1 = v1 + acc[ai][bj][m][1]; EPI_STORE_X8(v0, v1, o); }
;                 ss += __shfl_xor(ss, 16); ss += __shfl_xor(ss, 32);
;                 if (fq == 0) SSQ[(size_t)r * NPART + u.pn * 4 + wc] = ss;
;                 if (m == 3) asm volatile("" ::: "memory"); }
.LBB0_579:
	s_or_b64 exec, exec, s[0:1]
	v_add_u32_e32 v32, 0xa0, v134
	s_waitcnt lgkmcnt(0)
	v_ashrrev_i32_e32 v33, 31, v32
	v_lshlrev_b64 v[34:35], 11, v[32:33]
	v_lshl_add_u64 v[34:35], v[34:35], 0, v[132:133]
	v_lshlrev_b64 v[38:39], 1, v[34:35]
	v_lshl_add_u64 v[40:41], s[18:19], 0, v[38:39]
	s_waitcnt vmcnt(21)
	v_mov_b32_e32 v34, v212
	v_mov_b32_e32 v35, v213
	v_mov_b32_e32 v36, v214
	v_mov_b32_e32 v37, v215
	v_lshlrev_b32_e32 v42, 16, v34
	v_and_b32_e32 v43, 0xffff0000, v34
	v_lshlrev_b32_e32 v34, 16, v35
	v_and_b32_e32 v35, 0xffff0000, v35
	v_lshlrev_b32_e32 v44, 16, v36
	v_and_b32_e32 v45, 0xffff0000, v36
	v_lshlrev_b32_e32 v36, 16, v37
	v_and_b32_e32 v37, 0xffff0000, v37
	v_pk_add_f32 v[34:35], v[30:31], v[34:35]
	v_pk_add_f32 v[42:43], v[28:29], v[42:43]
	v_pk_add_f32 v[36:37], v[26:27], v[36:37]
	v_pk_add_f32 v[44:45], v[24:25], v[44:45]
	v_cvt_pk_bf16_f32 v24, v42, v43
	v_cvt_pk_bf16_f32 v25, v34, v35
	v_mul_f32_e32 v35, v35, v35
	v_cvt_pk_bf16_f32 v26, v44, v45
	v_cvt_pk_bf16_f32 v27, v36, v37
	v_mul_f32_e32 v40, v43, v43
	v_mul_f32_e32 v41, v45, v45
	v_mul_f32_e32 v37, v37, v37
	v_fmac_f32_e32 v40, v42, v42
	v_fmac_f32_e32 v35, v34, v34
	v_fmac_f32_e32 v41, v44, v44
	v_fmac_f32_e32 v37, v36, v36
	v_add_f32_e32 v34, v40, v35
	v_add_f32_e32 v35, v41, v37
	v_add_f32_e32 v40, v34, v35
	s_waitcnt vmcnt(20)
	v_mov_b32_e32 v28, v216
	v_mov_b32_e32 v29, v217
	v_mov_b32_e32 v30, v218
	v_mov_b32_e32 v31, v219
	v_lshlrev_b32_e32 v34, 16, v28
	v_and_b32_e32 v35, 0xffff0000, v28
	v_lshlrev_b32_e32 v28, 16, v29
	v_and_b32_e32 v29, 0xffff0000, v29
	v_lshlrev_b32_e32 v36, 16, v30
	v_and_b32_e32 v37, 0xffff0000, v30
	v_lshlrev_b32_e32 v30, 16, v31
	v_and_b32_e32 v31, 0xffff0000, v31
	v_pk_add_f32 v[22:23], v[22:23], v[28:29]
	v_pk_add_f32 v[20:21], v[20:21], v[34:35]
	v_pk_add_f32 v[28:29], v[18:19], v[30:31]
	v_pk_add_f32 v[30:31], v[16:17], v[36:37]
	v_mul_f32_e32 v16, v21, v21
	v_mul_f32_e32 v17, v23, v23
	v_mul_f32_e32 v18, v31, v31
	v_mul_f32_e32 v19, v29, v29
	v_fmac_f32_e32 v16, v20, v20
	v_fmac_f32_e32 v17, v22, v22
	v_fmac_f32_e32 v18, v30, v30
	v_fmac_f32_e32 v19, v28, v28
	v_add_f32_e32 v16, v16, v17
	v_add_f32_e32 v17, v18, v19
	v_add_f32_e32 v16, v16, v17
	v_add_f32_e32 v16, v40, v16
	ds_bpermute_b32 v17, v120, v16
	v_lshl_add_u64 v[34:35], s[20:21], 0, v[38:39]
	global_store_dwordx4 v[34:35], v[24:27], off
	v_cvt_pk_bf16_f32 v18, v20, v21
	v_cvt_pk_bf16_f32 v19, v22, v23
	s_waitcnt lgkmcnt(0)
	v_add_f32_e32 v16, v16, v17
	ds_bpermute_b32 v17, v114, v16
	v_cvt_pk_bf16_f32 v20, v30, v31
	v_cvt_pk_bf16_f32 v21, v28, v29
	global_store_dwordx4 v[34:35], v[18:21], off offset:256
	s_and_saveexec_b64 s[0:1], vcc
	s_cbranch_execz .LBB0_581
	s_waitcnt lgkmcnt(0)
	v_add_f32_e32 v18, v16, v17
	v_lshlrev_b64 v[16:17], 7, v[32:33]
	v_lshl_add_u64 v[16:17], s[22:23], 0, v[16:17]
	v_lshl_add_u64 v[16:17], s[14:15], 2, v[16:17]
	s_lshl_b32 s16, s40, 2
	v_lshl_add_u64 v[16:17], v[16:17], 0, s[16:17]
	global_store_dword v[16:17], v18, off
.LBB0_581:
	s_or_b64 exec, exec, s[0:1]
	v_add_u32_e32 v16, 0xb0, v134
	s_waitcnt lgkmcnt(0)
	v_ashrrev_i32_e32 v17, 31, v16
	v_lshlrev_b64 v[18:19], 11, v[16:17]
	v_lshl_add_u64 v[18:19], v[18:19], 0, v[132:133]
	v_lshlrev_b64 v[22:23], 1, v[18:19]
	v_lshl_add_u64 v[24:25], s[18:19], 0, v[22:23]
	s_waitcnt vmcnt(22)
	v_mov_b32_e32 v18, v220
	v_mov_b32_e32 v19, v221
	v_mov_b32_e32 v20, v222
	v_mov_b32_e32 v21, v223
	v_lshlrev_b32_e32 v26, 16, v18
	v_and_b32_e32 v27, 0xffff0000, v18
	v_lshlrev_b32_e32 v18, 16, v19
	v_and_b32_e32 v19, 0xffff0000, v19
	v_lshlrev_b32_e32 v28, 16, v20
	v_and_b32_e32 v29, 0xffff0000, v20
	v_lshlrev_b32_e32 v20, 16, v21
	v_and_b32_e32 v21, 0xffff0000, v21
	v_pk_add_f32 v[18:19], v[14:15], v[18:19]
	v_pk_add_f32 v[26:27], v[12:13], v[26:27]
	v_pk_add_f32 v[20:21], v[10:11], v[20:21]
	v_pk_add_f32 v[28:29], v[8:9], v[28:29]
	v_cvt_pk_bf16_f32 v8, v26, v27
	v_cvt_pk_bf16_f32 v9, v18, v19
	v_mul_f32_e32 v19, v19, v19
	v_cvt_pk_bf16_f32 v10, v28, v29
	v_cvt_pk_bf16_f32 v11, v20, v21
	v_mul_f32_e32 v24, v27, v27
	v_mul_f32_e32 v25, v29, v29
	v_mul_f32_e32 v21, v21, v21
	v_fmac_f32_e32 v24, v26, v26
	v_fmac_f32_e32 v19, v18, v18
	v_fmac_f32_e32 v25, v28, v28
	v_fmac_f32_e32 v21, v20, v20
	v_add_f32_e32 v18, v24, v19
	v_add_f32_e32 v19, v25, v21
	v_add_f32_e32 v24, v18, v19
	s_waitcnt vmcnt(21)
	v_mov_b32_e32 v12, v224
	v_mov_b32_e32 v13, v225
	v_mov_b32_e32 v14, v226
	v_mov_b32_e32 v15, v227
	v_lshlrev_b32_e32 v18, 16, v12
	v_and_b32_e32 v19, 0xffff0000, v12
	v_lshlrev_b32_e32 v12, 16, v13
	v_and_b32_e32 v13, 0xffff0000, v13
	v_lshlrev_b32_e32 v20, 16, v14
	v_and_b32_e32 v21, 0xffff0000, v14
	v_lshlrev_b32_e32 v14, 16, v15
	v_and_b32_e32 v15, 0xffff0000, v15
	v_pk_add_f32 v[6:7], v[6:7], v[12:13]
	v_pk_add_f32 v[4:5], v[4:5], v[18:19]
	v_pk_add_f32 v[12:13], v[2:3], v[14:15]
	v_pk_add_f32 v[14:15], v[0:1], v[20:21]
	v_mul_f32_e32 v0, v5, v5
	v_mul_f32_e32 v1, v7, v7
	v_mul_f32_e32 v2, v15, v15
	v_mul_f32_e32 v3, v13, v13
	v_fmac_f32_e32 v0, v4, v4
	v_fmac_f32_e32 v1, v6, v6
	v_fmac_f32_e32 v2, v14, v14
	v_fmac_f32_e32 v3, v12, v12
	v_add_f32_e32 v0, v0, v1
	v_add_f32_e32 v1, v2, v3
	v_add_f32_e32 v0, v0, v1
	v_add_f32_e32 v0, v24, v0
	ds_bpermute_b32 v1, v120, v0
	v_lshl_add_u64 v[18:19], s[20:21], 0, v[22:23]
	global_store_dwordx4 v[18:19], v[8:11], off
	v_cvt_pk_bf16_f32 v2, v4, v5
	v_cvt_pk_bf16_f32 v3, v6, v7
	s_waitcnt lgkmcnt(0)
	v_add_f32_e32 v0, v0, v1
	ds_bpermute_b32 v1, v114, v0
	v_cvt_pk_bf16_f32 v4, v14, v15
	v_cvt_pk_bf16_f32 v5, v12, v13
	global_store_dwordx4 v[18:19], v[2:5], off offset:256
	s_and_saveexec_b64 s[0:1], vcc
	s_cbranch_execz .LBB0_583
	s_waitcnt lgkmcnt(0)
	v_add_f32_e32 v2, v0, v1
	v_lshlrev_b64 v[0:1], 7, v[16:17]
	v_lshl_add_u64 v[0:1], s[22:23], 0, v[0:1]
	v_lshl_add_u64 v[0:1], s[14:15], 2, v[0:1]
	s_lshl_b32 s16, s40, 2
	v_lshl_add_u64 v[0:1], v[0:1], 0, s[16:17]
	global_store_dword v[0:1], v2, off

; #define EPI_LOAD_X8(d0, d1, o) do { const u32x4 h_ = *(const u32x4*)(XBo + (o)); \
;         d0[0] = BFLO(h_.x); d0[1] = BFHI(h_.x); d0[2] = BFLO(h_.y); d0[3] = BFHI(h_.y); d1[0] = BFLO(h_.z); d1[1] = BFHI(h_.z); d1[2] = BFLO(h_.w); d1[3] = BFHI(h_.w); } while (0)
;     __device__ __forceinline__ void operator()(const f32x4 (&acc)[2][2][4][2], const Unit& u, int wr, int wc, int fr, int fq) const {
;         const int row0 = u.pm * BM + wr * 64 + fr, col0 = u.pn * BM + wc * 32 + 8 * fq;
; #pragma unroll
;         for (int ai = 0; ai < 2; ++ai)
; #pragma unroll
;             for (int m = 0; m < 4; ++m) { const int r = row0 + ai * HALF + m * 16; const size_t off = (size_t)r * DM + col0; float ss = 0.f;
; #pragma unroll
;                 for (int bj = 0; bj < 2; ++bj) { const size_t o = off + bj * HALF;
;                     f32x4 v0, v1; if (F32BASE) { v0 = *(const f32x4*)(base + o); v1 = *(const f32x4*)(base + o + 4); } else EPI_LOAD_X8(v0, v1, o);
;                     v0 = v0 + acc[ai][bj][m][0]; v1 = v1 + acc[ai][bj][m][1]; EPI_STORE_X8(v0, v1, o); }
;                 ss += __shfl_xor(ss, 16); ss += __shfl_xor(ss, 32);
;                 if (fq == 0) SSQ[(size_t)r * NPART + u.pn * 4 + wc] = ss;
;                 if (m == 3) asm volatile("" ::: "memory"); }
.LBB0_807:
	s_lshl_b32 s0, s53, 8
	s_add_i32 s0, s0, s43
	v_mbcnt_lo_u32_b32 v160, -1, 0
	v_mbcnt_hi_u32_b32 v160, -1, v160
	v_xor_b32_e32 v161, 32, v145
	v_and_or_b32 v134, v160, 15, s0
	s_lshl_b32 s0, s16, 8
	v_ashrrev_i32_e32 v132, 1, v160
	s_or_b32 s0, s0, s44
	v_and_b32_e32 v132, -8, v132
	v_add_u32_e32 v132, s0, v132
	v_ashrrev_i32_e32 v135, 31, v134
	v_ashrrev_i32_e32 v133, 31, v132
	v_lshlrev_b64 v[146:147], 11, v[134:135]
	v_lshl_add_u64 v[146:147], v[146:147], 0, v[132:133]
	v_lshlrev_b64 v[150:151], 1, v[146:147]
	v_lshl_add_u64 v[152:153], s[18:19], 0, v[150:151]
	global_load_dwordx4 v[164:167], v150, s[18:19]
	global_load_dwordx4 v[168:171], v150, s[18:19] offset:256
	s_add_u32 vcc_lo, s18, 0x10000
	s_addc_u32 vcc_hi, s19, 0
	global_load_dwordx4 v[172:175], v150, vcc
	global_load_dwordx4 v[176:179], v150, vcc offset:256
	s_add_u32 s0, s18, 0x20000
	s_addc_u32 s1, s19, 0
	global_load_dwordx4 v[180:183], v150, s[0:1]
	global_load_dwordx4 v[184:187], v150, s[0:1] offset:256
	s_add_u32 vcc_lo, s18, 0x30000
	s_addc_u32 vcc_hi, s19, 0
	global_load_dwordx4 v[188:191], v150, vcc
	global_load_dwordx4 v[192:195], v150, vcc offset:256
	s_add_u32 s0, s18, 0x80000
	s_addc_u32 s1, s19, 0
	global_load_dwordx4 v[196:199], v150, s[0:1]
	global_load_dwordx4 v[200:203], v150, s[0:1] offset:256
	s_add_u32 vcc_lo, s18, 0x90000
	s_addc_u32 vcc_hi, s19, 0
	global_load_dwordx4 v[204:207], v150, vcc
	global_load_dwordx4 v[208:211], v150, vcc offset:256
	s_add_u32 s0, s18, 0xa0000
	s_addc_u32 s1, s19, 0
	global_load_dwordx4 v[212:215], v150, s[0:1]
	global_load_dwordx4 v[216:219], v150, s[0:1] offset:256
	s_add_u32 vcc_lo, s18, 0xb0000
	s_addc_u32 vcc_hi, s19, 0
	global_load_dwordx4 v[220:223], v150, vcc
	global_load_dwordx4 v[224:227], v150, vcc offset:256
	s_lshl_b32 s14, s16, 2
	v_cmp_gt_u32_e32 vcc, 16, v160
	s_ashr_i32 s15, s14, 31
	s_waitcnt vmcnt(15)
	v_mov_b32_e32 v146, v164
	v_mov_b32_e32 v147, v165
	v_mov_b32_e32 v148, v166
	v_mov_b32_e32 v149, v167
	v_lshlrev_b32_e32 v154, 16, v146
	v_and_b32_e32 v155, 0xffff0000, v146
	v_lshlrev_b32_e32 v146, 16, v147
	v_and_b32_e32 v147, 0xffff0000, v147
	v_lshlrev_b32_e32 v156, 16, v148
	v_and_b32_e32 v157, 0xffff0000, v148
	v_lshlrev_b32_e32 v148, 16, v149
	v_and_b32_e32 v149, 0xffff0000, v149
	v_pk_add_f32 v[126:127], v[126:127], v[146:147]
	v_pk_add_f32 v[154:155], v[124:125], v[154:155]
	v_pk_add_f32 v[158:159], v[122:123], v[148:149]
	v_pk_add_f32 v[156:157], v[120:121], v[156:157]
	v_cvt_pk_bf16_f32 v122, v154, v155
	v_cvt_pk_bf16_f32 v123, v126, v127
	v_mul_f32_e32 v127, v127, v127
	v_cvt_pk_bf16_f32 v124, v156, v157
	v_cvt_pk_bf16_f32 v125, v158, v159
	v_mul_f32_e32 v152, v155, v155
	v_mul_f32_e32 v153, v157, v157
	v_mul_f32_e32 v155, v159, v159
	v_fmac_f32_e32 v152, v154, v154
	v_fmac_f32_e32 v127, v126, v126
	v_fmac_f32_e32 v153, v156, v156
	v_fmac_f32_e32 v155, v158, v158
	v_add_f32_e32 v126, v152, v127
	v_add_f32_e32 v127, v153, v155
	v_add_f32_e32 v154, v126, v127
	v_and_b32_e32 v121, 64, v145
	v_xor_b32_e32 v120, 16, v145
	v_add_u32_e32 v121, 64, v121
	v_cmp_lt_i32_e64 s[0:1], v120, v121
	s_waitcnt vmcnt(14)
	v_mov_b32_e32 v146, v168
	v_mov_b32_e32 v147, v169
	v_mov_b32_e32 v148, v170
	v_mov_b32_e32 v149, v171
	v_lshlrev_b32_e32 v126, 16, v146
	v_and_b32_e32 v127, 0xffff0000, v146
	v_lshlrev_b32_e32 v146, 16, v147
	v_and_b32_e32 v147, 0xffff0000, v147
	v_lshlrev_b32_e32 v152, 16, v148
	v_and_b32_e32 v153, 0xffff0000, v148
	v_lshlrev_b32_e32 v148, 16, v149
	v_and_b32_e32 v149, 0xffff0000, v149
	v_pk_add_f32 v[118:119], v[118:119], v[146:147]
	v_pk_add_f32 v[116:117], v[116:117], v[126:127]
	v_pk_add_f32 v[126:127], v[114:115], v[148:149]
	v_pk_add_f32 v[146:147], v[112:113], v[152:153]
	v_mul_f32_e32 v112, v117, v117
	v_mul_f32_e32 v113, v119, v119
	v_mul_f32_e32 v114, v147, v147
	v_mul_f32_e32 v115, v127, v127
	v_fmac_f32_e32 v112, v116, v116
	v_fmac_f32_e32 v113, v118, v118
	v_fmac_f32_e32 v114, v146, v146
	v_fmac_f32_e32 v115, v126, v126
	v_add_f32_e32 v112, v112, v113
	v_add_f32_e32 v113, v114, v115
	v_cndmask_b32_e64 v120, v145, v120, s[0:1]
	v_add_f32_e32 v112, v112, v113
	v_lshlrev_b32_e32 v120, 2, v120
	v_add_f32_e32 v112, v154, v112
	ds_bpermute_b32 v113, v120, v112
	v_cmp_lt_i32_e64 s[0:1], v161, v121
	v_lshl_add_u64 v[148:149], s[20:21], 0, v[150:151]
	global_store_dwordx4 v[148:149], v[122:125], off
	v_cndmask_b32_e64 v114, v145, v161, s[0:1]
	s_waitcnt lgkmcnt(0)
	v_add_f32_e32 v112, v112, v113
	v_lshlrev_b32_e32 v114, 2, v114
	ds_bpermute_b32 v113, v114, v112
	v_cvt_pk_bf16_f32 v116, v116, v117
	v_cvt_pk_bf16_f32 v117, v118, v119
	v_cvt_pk_bf16_f32 v118, v146, v147
	v_cvt_pk_bf16_f32 v119, v126, v127
	global_store_dwordx4 v[148:149], v[116:119], off offset:256
	s_and_saveexec_b64 s[0:1], vcc
	s_cbranch_execz .LBB0_809
	s_waitcnt lgkmcnt(0)
	v_add_f32_e32 v115, v112, v113
	v_lshlrev_b64 v[112:113], 7, v[134:135]
	v_lshl_add_u64 v[112:113], s[22:23], 0, v[112:113]
	v_lshl_add_u64 v[112:113], s[14:15], 2, v[112:113]
	s_lshl_b32 s16, s42, 2
	v_lshl_add_u64 v[112:113], v[112:113], 0, s[16:17]
	global_store_dword v[112:113], v115, off
; #define EPI_LOAD_X8(d0, d1, o) do { const u32x4 h_ = *(const u32x4*)(XBo + (o)); \
;         d0[0] = BFLO(h_.x); d0[1] = BFHI(h_.x); d0[2] = BFLO(h_.y); d0[3] = BFHI(h_.y); d1[0] = BFLO(h_.z); d1[1] = BFHI(h_.z); d1[2] = BFLO(h_.w); d1[3] = BFHI(h_.w); } while (0)
;     __device__ __forceinline__ void operator()(const f32x4 (&acc)[2][2][4][2], const Unit& u, int wr, int wc, int fr, int fq) const {
;     ...
;             for (int m = 0; m < 4; ++m) { const int r = row0 + ai * HALF + m * 16; const size_t off = (size_t)r * DM + col0; float ss = 0.f;
; #pragma unroll
;                 for (int bj = 0; bj < 2; ++bj) { const size_t o = off + bj * HALF;
;                     f32x4 v0, v1; if (F32BASE) { v0 = *(const f32x4*)(base + o); v1 = *(const f32x4*)(base + o + 4); } else EPI_LOAD_X8(v0, v1, o);
;                     v0 = v0 + acc[ai][bj][m][0]; v1 = v1 + acc[ai][bj][m][1]; EPI_STORE_X8(v0, v1, o); }
;                 ss += __shfl_xor(ss, 16); ss += __shfl_xor(ss, 32);
;                 if (fq == 0) SSQ[(size_t)r * NPART + u.pn * 4 + wc] = ss;
;                 if (m == 3) asm volatile("" ::: "memory"); }
.LBB0_809:
	s_or_b64 exec, exec, s[0:1]
	v_or_b32_e32 v112, 16, v134
	s_waitcnt lgkmcnt(0)
	v_ashrrev_i32_e32 v113, 31, v112
	v_lshlrev_b64 v[116:117], 11, v[112:113]
	v_lshl_add_u64 v[116:117], v[116:117], 0, v[132:133]
	v_lshlrev_b64 v[122:123], 1, v[116:117]
	v_lshl_add_u64 v[124:125], s[18:19], 0, v[122:123]
	s_waitcnt vmcnt(16)
	v_mov_b32_e32 v116, v172
	v_mov_b32_e32 v117, v173
	v_mov_b32_e32 v118, v174
	v_mov_b32_e32 v119, v175
	v_lshlrev_b32_e32 v126, 16, v116
	v_and_b32_e32 v127, 0xffff0000, v116
	v_lshlrev_b32_e32 v116, 16, v117
	v_and_b32_e32 v117, 0xffff0000, v117
	v_lshlrev_b32_e32 v146, 16, v118
	v_and_b32_e32 v147, 0xffff0000, v118
	v_lshlrev_b32_e32 v118, 16, v119
	v_and_b32_e32 v119, 0xffff0000, v119
	v_pk_add_f32 v[116:117], v[110:111], v[116:117]
	v_pk_add_f32 v[126:127], v[108:109], v[126:127]
	v_pk_add_f32 v[118:119], v[106:107], v[118:119]
	v_pk_add_f32 v[146:147], v[104:105], v[146:147]
	v_cvt_pk_bf16_f32 v104, v126, v127
	v_cvt_pk_bf16_f32 v105, v116, v117
	v_mul_f32_e32 v115, v127, v127
	v_cvt_pk_bf16_f32 v106, v146, v147
	v_cvt_pk_bf16_f32 v107, v118, v119
	v_mul_f32_e32 v117, v117, v117
	v_mul_f32_e32 v121, v147, v147
	v_mul_f32_e32 v119, v119, v119
	v_fmac_f32_e32 v115, v126, v126
	v_fmac_f32_e32 v117, v116, v116
	v_fmac_f32_e32 v121, v146, v146
	v_fmac_f32_e32 v119, v118, v118
	v_add_f32_e32 v115, v115, v117
	v_add_f32_e32 v116, v121, v119
	v_add_f32_e32 v115, v115, v116
	s_waitcnt vmcnt(15)
	v_mov_b32_e32 v108, v176
	v_mov_b32_e32 v109, v177
	v_mov_b32_e32 v110, v178
	v_mov_b32_e32 v111, v179
	v_lshlrev_b32_e32 v116, 16, v108
	v_and_b32_e32 v117, 0xffff0000, v108
	v_lshlrev_b32_e32 v108, 16, v109
	v_and_b32_e32 v109, 0xffff0000, v109
	v_lshlrev_b32_e32 v118, 16, v110
	v_and_b32_e32 v119, 0xffff0000, v110
	v_lshlrev_b32_e32 v110, 16, v111
	v_and_b32_e32 v111, 0xffff0000, v111
	v_pk_add_f32 v[102:103], v[102:103], v[108:109]
	v_pk_add_f32 v[100:101], v[100:101], v[116:117]
	v_pk_add_f32 v[108:109], v[98:99], v[110:111]
	v_pk_add_f32 v[110:111], v[96:97], v[118:119]
	v_mul_f32_e32 v96, v101, v101
	v_mul_f32_e32 v97, v103, v103
	v_mul_f32_e32 v98, v111, v111
	v_mul_f32_e32 v99, v109, v109
	v_fmac_f32_e32 v96, v100, v100
	v_fmac_f32_e32 v97, v102, v102
	v_fmac_f32_e32 v98, v110, v110
	v_fmac_f32_e32 v99, v108, v108
	v_add_f32_e32 v96, v96, v97
	v_add_f32_e32 v97, v98, v99
	v_add_f32_e32 v96, v96, v97
	v_add_f32_e32 v96, v115, v96
	ds_bpermute_b32 v97, v120, v96
	v_lshl_add_u64 v[116:117], s[20:21], 0, v[122:123]
	global_store_dwordx4 v[116:117], v[104:107], off
	v_cvt_pk_bf16_f32 v98, v100, v101
	v_cvt_pk_bf16_f32 v99, v102, v103
	s_waitcnt lgkmcnt(0)
	v_add_f32_e32 v96, v96, v97
	ds_bpermute_b32 v97, v114, v96
	v_cvt_pk_bf16_f32 v100, v110, v111
	v_cvt_pk_bf16_f32 v101, v108, v109
	global_store_dwordx4 v[116:117], v[98:101], off offset:256
	s_and_saveexec_b64 s[0:1], vcc
	s_cbranch_execz .LBB0_811
	s_waitcnt lgkmcnt(0)
	v_add_f32_e32 v98, v96, v97
	v_lshlrev_b64 v[96:97], 7, v[112:113]
	v_lshl_add_u64 v[96:97], s[22:23], 0, v[96:97]
	v_lshl_add_u64 v[96:97], s[14:15], 2, v[96:97]
	s_lshl_b32 s16, s42, 2
	v_lshl_add_u64 v[96:97], v[96:97], 0, s[16:17]
	global_store_dword v[96:97], v98, off
.LBB0_811:
	s_or_b64 exec, exec, s[0:1]
	v_or_b32_e32 v96, 32, v134
	s_waitcnt lgkmcnt(0)
	v_ashrrev_i32_e32 v97, 31, v96
	v_lshlrev_b64 v[98:99], 11, v[96:97]
	v_lshl_add_u64 v[98:99], v[98:99], 0, v[132:133]
	v_lshlrev_b64 v[102:103], 1, v[98:99]
	v_lshl_add_u64 v[104:105], s[18:19], 0, v[102:103]
	s_waitcnt vmcnt(17)
	v_mov_b32_e32 v98, v180
	v_mov_b32_e32 v99, v181
	v_mov_b32_e32 v100, v182
	v_mov_b32_e32 v101, v183
	v_lshlrev_b32_e32 v106, 16, v98
	v_and_b32_e32 v107, 0xffff0000, v98
	v_lshlrev_b32_e32 v98, 16, v99
	v_and_b32_e32 v99, 0xffff0000, v99
	v_lshlrev_b32_e32 v108, 16, v100
	v_and_b32_e32 v109, 0xffff0000, v100
	v_lshlrev_b32_e32 v100, 16, v101
	v_and_b32_e32 v101, 0xffff0000, v101
	v_pk_add_f32 v[98:99], v[94:95], v[98:99]
	v_pk_add_f32 v[106:107], v[92:93], v[106:107]
	v_pk_add_f32 v[100:101], v[90:91], v[100:101]
	v_pk_add_f32 v[108:109], v[88:89], v[108:109]
	v_cvt_pk_bf16_f32 v88, v106, v107
	v_cvt_pk_bf16_f32 v89, v98, v99
	v_mul_f32_e32 v99, v99, v99
	v_cvt_pk_bf16_f32 v90, v108, v109
	v_cvt_pk_bf16_f32 v91, v100, v101
	v_mul_f32_e32 v104, v107, v107
	v_mul_f32_e32 v105, v109, v109
	v_mul_f32_e32 v101, v101, v101
	v_fmac_f32_e32 v104, v106, v106
	v_fmac_f32_e32 v99, v98, v98
	v_fmac_f32_e32 v105, v108, v108
	v_fmac_f32_e32 v101, v100, v100
	v_add_f32_e32 v98, v104, v99
	v_add_f32_e32 v99, v105, v101
	v_add_f32_e32 v104, v98, v99
	s_waitcnt vmcnt(16)
	v_mov_b32_e32 v92, v184
	v_mov_b32_e32 v93, v185
	v_mov_b32_e32 v94, v186
	v_mov_b32_e32 v95, v187
	v_lshlrev_b32_e32 v98, 16, v92
	v_and_b32_e32 v99, 0xffff0000, v92
	v_lshlrev_b32_e32 v92, 16, v93
	v_and_b32_e32 v93, 0xffff0000, v93
	v_lshlrev_b32_e32 v100, 16, v94
	v_and_b32_e32 v101, 0xffff0000, v94
	v_lshlrev_b32_e32 v94, 16, v95
	v_and_b32_e32 v95, 0xffff0000, v95
	v_pk_add_f32 v[86:87], v[86:87], v[92:93]
	v_pk_add_f32 v[84:85], v[84:85], v[98:99]
	v_pk_add_f32 v[92:93], v[82:83], v[94:95]
	v_pk_add_f32 v[94:95], v[80:81], v[100:101]
	v_mul_f32_e32 v80, v85, v85
	v_mul_f32_e32 v81, v87, v87
	v_mul_f32_e32 v82, v95, v95
	v_mul_f32_e32 v83, v93, v93
	v_fmac_f32_e32 v80, v84, v84
	v_fmac_f32_e32 v81, v86, v86
	v_fmac_f32_e32 v82, v94, v94
	v_fmac_f32_e32 v83, v92, v92
	v_add_f32_e32 v80, v80, v81
	v_add_f32_e32 v81, v82, v83
	v_add_f32_e32 v80, v80, v81
	v_add_f32_e32 v80, v104, v80
	ds_bpermute_b32 v81, v120, v80
	v_lshl_add_u64 v[98:99], s[20:21], 0, v[102:103]
	global_store_dwordx4 v[98:99], v[88:91], off
	v_cvt_pk_bf16_f32 v82, v84, v85
	v_cvt_pk_bf16_f32 v83, v86, v87
	s_waitcnt lgkmcnt(0)
	v_add_f32_e32 v80, v80, v81
	ds_bpermute_b32 v81, v114, v80
	v_cvt_pk_bf16_f32 v84, v94, v95
	v_cvt_pk_bf16_f32 v85, v92, v93
	global_store_dwordx4 v[98:99], v[82:85], off offset:256
	s_and_saveexec_b64 s[0:1], vcc
	s_cbranch_execz .LBB0_813
	s_waitcnt lgkmcnt(0)
	v_add_f32_e32 v82, v80, v81
	v_lshlrev_b64 v[80:81], 7, v[96:97]
	v_lshl_add_u64 v[80:81], s[22:23], 0, v[80:81]
	v_lshl_add_u64 v[80:81], s[14:15], 2, v[80:81]
	s_lshl_b32 s16, s42, 2
	v_lshl_add_u64 v[80:81], v[80:81], 0, s[16:17]
	global_store_dword v[80:81], v82, off
; #define EPI_LOAD_X8(d0, d1, o) do { const u32x4 h_ = *(const u32x4*)(XBo + (o)); \
;         d0[0] = BFLO(h_.x); d0[1] = BFHI(h_.x); d0[2] = BFLO(h_.y); d0[3] = BFHI(h_.y); d1[0] = BFLO(h_.z); d1[1] = BFHI(h_.z); d1[2] = BFLO(h_.w); d1[3] = BFHI(h_.w); } while (0)
;     __device__ __forceinline__ void operator()(const f32x4 (&acc)[2][2][4][2], const Unit& u, int wr, int wc, int fr, int fq) const {
;     ...
;             for (int m = 0; m < 4; ++m) { const int r = row0 + ai * HALF + m * 16; const size_t off = (size_t)r * DM + col0; float ss = 0.f;
; #pragma unroll
;                 for (int bj = 0; bj < 2; ++bj) { const size_t o = off + bj * HALF;
;                     f32x4 v0, v1; if (F32BASE) { v0 = *(const f32x4*)(base + o); v1 = *(const f32x4*)(base + o + 4); } else EPI_LOAD_X8(v0, v1, o);
;                     v0 = v0 + acc[ai][bj][m][0]; v1 = v1 + acc[ai][bj][m][1]; EPI_STORE_X8(v0, v1, o); }
;                 ss += __shfl_xor(ss, 16); ss += __shfl_xor(ss, 32);
;                 if (fq == 0) SSQ[(size_t)r * NPART + u.pn * 4 + wc] = ss;
;                 if (m == 3) asm volatile("" ::: "memory"); }
.LBB0_813:
	s_or_b64 exec, exec, s[0:1]
	v_or_b32_e32 v80, 48, v134
	s_waitcnt lgkmcnt(0)
	v_ashrrev_i32_e32 v81, 31, v80
	v_lshlrev_b64 v[82:83], 11, v[80:81]
	v_lshl_add_u64 v[82:83], v[82:83], 0, v[132:133]
	v_lshlrev_b64 v[86:87], 1, v[82:83]
	v_lshl_add_u64 v[88:89], s[18:19], 0, v[86:87]
	s_waitcnt vmcnt(18)
	v_mov_b32_e32 v82, v188
	v_mov_b32_e32 v83, v189
	v_mov_b32_e32 v84, v190
	v_mov_b32_e32 v85, v191
	v_lshlrev_b32_e32 v90, 16, v82
	v_and_b32_e32 v91, 0xffff0000, v82
	v_lshlrev_b32_e32 v82, 16, v83
	v_and_b32_e32 v83, 0xffff0000, v83
	v_lshlrev_b32_e32 v92, 16, v84
	v_and_b32_e32 v93, 0xffff0000, v84
	v_lshlrev_b32_e32 v84, 16, v85
	v_and_b32_e32 v85, 0xffff0000, v85
	v_pk_add_f32 v[82:83], v[78:79], v[82:83]
	v_pk_add_f32 v[90:91], v[76:77], v[90:91]
	v_pk_add_f32 v[84:85], v[74:75], v[84:85]
	v_pk_add_f32 v[92:93], v[72:73], v[92:93]
	v_cvt_pk_bf16_f32 v72, v90, v91
	v_cvt_pk_bf16_f32 v73, v82, v83
	v_mul_f32_e32 v83, v83, v83
	v_cvt_pk_bf16_f32 v74, v92, v93
	v_cvt_pk_bf16_f32 v75, v84, v85
	v_mul_f32_e32 v88, v91, v91
	v_mul_f32_e32 v89, v93, v93
	v_mul_f32_e32 v85, v85, v85
	v_fmac_f32_e32 v88, v90, v90
	v_fmac_f32_e32 v83, v82, v82
	v_fmac_f32_e32 v89, v92, v92
	v_fmac_f32_e32 v85, v84, v84
	v_add_f32_e32 v82, v88, v83
	v_add_f32_e32 v83, v89, v85
	v_add_f32_e32 v88, v82, v83
	s_waitcnt vmcnt(17)
	v_mov_b32_e32 v76, v192
	v_mov_b32_e32 v77, v193
	v_mov_b32_e32 v78, v194
	v_mov_b32_e32 v79, v195
	v_lshlrev_b32_e32 v82, 16, v76
	v_and_b32_e32 v83, 0xffff0000, v76
	v_lshlrev_b32_e32 v76, 16, v77
	v_and_b32_e32 v77, 0xffff0000, v77
	v_lshlrev_b32_e32 v84, 16, v78
	v_and_b32_e32 v85, 0xffff0000, v78
	v_lshlrev_b32_e32 v78, 16, v79
	v_and_b32_e32 v79, 0xffff0000, v79
	v_pk_add_f32 v[70:71], v[70:71], v[76:77]
	v_pk_add_f32 v[68:69], v[68:69], v[82:83]
	v_pk_add_f32 v[76:77], v[66:67], v[78:79]
	v_pk_add_f32 v[78:79], v[64:65], v[84:85]
	v_mul_f32_e32 v64, v69, v69
	v_mul_f32_e32 v65, v71, v71
	v_mul_f32_e32 v66, v79, v79
	v_mul_f32_e32 v67, v77, v77
	v_fmac_f32_e32 v64, v68, v68
	v_fmac_f32_e32 v65, v70, v70
	v_fmac_f32_e32 v66, v78, v78
	v_fmac_f32_e32 v67, v76, v76
	v_add_f32_e32 v64, v64, v65
	v_add_f32_e32 v65, v66, v67
	v_add_f32_e32 v64, v64, v65
	v_add_f32_e32 v64, v88, v64
	ds_bpermute_b32 v65, v120, v64
	v_lshl_add_u64 v[82:83], s[20:21], 0, v[86:87]
	global_store_dwordx4 v[82:83], v[72:75], off
	v_cvt_pk_bf16_f32 v66, v68, v69
	v_cvt_pk_bf16_f32 v67, v70, v71
	s_waitcnt lgkmcnt(0)
	v_add_f32_e32 v64, v64, v65
	ds_bpermute_b32 v65, v114, v64
	v_cvt_pk_bf16_f32 v68, v78, v79
	v_cvt_pk_bf16_f32 v69, v76, v77
	global_store_dwordx4 v[82:83], v[66:69], off offset:256
	s_and_saveexec_b64 s[0:1], vcc
	s_cbranch_execz .LBB0_815
	s_waitcnt lgkmcnt(0)
	v_add_f32_e32 v66, v64, v65
	v_lshlrev_b64 v[64:65], 7, v[80:81]
	v_lshl_add_u64 v[64:65], s[22:23], 0, v[64:65]
	v_lshl_add_u64 v[64:65], s[14:15], 2, v[64:65]
	s_lshl_b32 s16, s42, 2
	v_lshl_add_u64 v[64:65], v[64:65], 0, s[16:17]
	global_store_dword v[64:65], v66, off
.LBB0_815:
	s_or_b64 exec, exec, s[0:1]
	v_add_u32_e32 v64, 0x80, v134
	s_waitcnt lgkmcnt(0)
	v_ashrrev_i32_e32 v65, 31, v64
	v_lshlrev_b64 v[66:67], 11, v[64:65]
	v_lshl_add_u64 v[66:67], v[66:67], 0, v[132:133]
	v_lshlrev_b64 v[70:71], 1, v[66:67]
	v_lshl_add_u64 v[72:73], s[18:19], 0, v[70:71]
	s_waitcnt vmcnt(19)
	v_mov_b32_e32 v66, v196
	v_mov_b32_e32 v67, v197
	v_mov_b32_e32 v68, v198
	v_mov_b32_e32 v69, v199
	v_lshlrev_b32_e32 v74, 16, v66
	v_and_b32_e32 v75, 0xffff0000, v66
	v_lshlrev_b32_e32 v66, 16, v67
	v_and_b32_e32 v67, 0xffff0000, v67
	v_lshlrev_b32_e32 v76, 16, v68
	v_and_b32_e32 v77, 0xffff0000, v68
	v_lshlrev_b32_e32 v68, 16, v69
	v_and_b32_e32 v69, 0xffff0000, v69
	v_pk_add_f32 v[66:67], v[62:63], v[66:67]
	v_pk_add_f32 v[74:75], v[60:61], v[74:75]
	v_pk_add_f32 v[68:69], v[58:59], v[68:69]
	v_pk_add_f32 v[76:77], v[56:57], v[76:77]
	v_cvt_pk_bf16_f32 v56, v74, v75
	v_cvt_pk_bf16_f32 v57, v66, v67
	v_mul_f32_e32 v67, v67, v67
	v_cvt_pk_bf16_f32 v58, v76, v77
	v_cvt_pk_bf16_f32 v59, v68, v69
	v_mul_f32_e32 v72, v75, v75
	v_mul_f32_e32 v73, v77, v77
	v_mul_f32_e32 v69, v69, v69
	v_fmac_f32_e32 v72, v74, v74
	v_fmac_f32_e32 v67, v66, v66
	v_fmac_f32_e32 v73, v76, v76
	v_fmac_f32_e32 v69, v68, v68
	v_add_f32_e32 v66, v72, v67
	v_add_f32_e32 v67, v73, v69
	v_add_f32_e32 v72, v66, v67
	s_waitcnt vmcnt(18)
	v_mov_b32_e32 v60, v200
	v_mov_b32_e32 v61, v201
	v_mov_b32_e32 v62, v202
	v_mov_b32_e32 v63, v203
	v_lshlrev_b32_e32 v66, 16, v60
	v_and_b32_e32 v67, 0xffff0000, v60
	v_lshlrev_b32_e32 v60, 16, v61
	v_and_b32_e32 v61, 0xffff0000, v61
	v_lshlrev_b32_e32 v68, 16, v62
	v_and_b32_e32 v69, 0xffff0000, v62
	v_lshlrev_b32_e32 v62, 16, v63
	v_and_b32_e32 v63, 0xffff0000, v63
	v_pk_add_f32 v[54:55], v[54:55], v[60:61]
	v_pk_add_f32 v[52:53], v[52:53], v[66:67]
	v_pk_add_f32 v[60:61], v[50:51], v[62:63]
	v_pk_add_f32 v[62:63], v[48:49], v[68:69]
	v_mul_f32_e32 v48, v53, v53
	v_mul_f32_e32 v49, v55, v55
	v_mul_f32_e32 v50, v63, v63
	v_mul_f32_e32 v51, v61, v61
	v_fmac_f32_e32 v48, v52, v52
	v_fmac_f32_e32 v49, v54, v54
	v_fmac_f32_e32 v50, v62, v62
	v_fmac_f32_e32 v51, v60, v60
	v_add_f32_e32 v48, v48, v49
	v_add_f32_e32 v49, v50, v51
	v_add_f32_e32 v48, v48, v49
	v_add_f32_e32 v48, v72, v48
	ds_bpermute_b32 v49, v120, v48
	v_lshl_add_u64 v[66:67], s[20:21], 0, v[70:71]
	global_store_dwordx4 v[66:67], v[56:59], off
	v_cvt_pk_bf16_f32 v50, v52, v53
	v_cvt_pk_bf16_f32 v51, v54, v55
	s_waitcnt lgkmcnt(0)
	v_add_f32_e32 v48, v48, v49
	ds_bpermute_b32 v49, v114, v48
	v_cvt_pk_bf16_f32 v52, v62, v63
	v_cvt_pk_bf16_f32 v53, v60, v61
	global_store_dwordx4 v[66:67], v[50:53], off offset:256
	s_and_saveexec_b64 s[0:1], vcc
	s_cbranch_execz .LBB0_817
	s_waitcnt lgkmcnt(0)
	v_add_f32_e32 v50, v48, v49
	v_lshlrev_b64 v[48:49], 7, v[64:65]
	v_lshl_add_u64 v[48:49], s[22:23], 0, v[48:49]
	v_lshl_add_u64 v[48:49], s[14:15], 2, v[48:49]
	s_lshl_b32 s16, s42, 2
	v_lshl_add_u64 v[48:49], v[48:49], 0, s[16:17]
	global_store_dword v[48:49], v50, off
; #define EPI_LOAD_X8(d0, d1, o) do { const u32x4 h_ = *(const u32x4*)(XBo + (o)); \
;         d0[0] = BFLO(h_.x); d0[1] = BFHI(h_.x); d0[2] = BFLO(h_.y); d0[3] = BFHI(h_.y); d1[0] = BFLO(h_.z); d1[1] = BFHI(h_.z); d1[2] = BFLO(h_.w); d1[3] = BFHI(h_.w); } while (0)
;     __device__ __forceinline__ void operator()(const f32x4 (&acc)[2][2][4][2], const Unit& u, int wr, int wc, int fr, int fq) const {
;     ...
;             for (int m = 0; m < 4; ++m) { const int r = row0 + ai * HALF + m * 16; const size_t off = (size_t)r * DM + col0; float ss = 0.f;
; #pragma unroll
;                 for (int bj = 0; bj < 2; ++bj) { const size_t o = off + bj * HALF;
;                     f32x4 v0, v1; if (F32BASE) { v0 = *(const f32x4*)(base + o); v1 = *(const f32x4*)(base + o + 4); } else EPI_LOAD_X8(v0, v1, o);
;                     v0 = v0 + acc[ai][bj][m][0]; v1 = v1 + acc[ai][bj][m][1]; EPI_STORE_X8(v0, v1, o); }
;                 ss += __shfl_xor(ss, 16); ss += __shfl_xor(ss, 32);
;                 if (fq == 0) SSQ[(size_t)r * NPART + u.pn * 4 + wc] = ss;
.LBB0_817:
	s_or_b64 exec, exec, s[0:1]
	v_add_u32_e32 v48, 0x90, v134
	s_waitcnt lgkmcnt(0)
	v_ashrrev_i32_e32 v49, 31, v48
	v_lshlrev_b64 v[50:51], 11, v[48:49]
	v_lshl_add_u64 v[50:51], v[50:51], 0, v[132:133]
	v_lshlrev_b64 v[54:55], 1, v[50:51]
	v_lshl_add_u64 v[56:57], s[18:19], 0, v[54:55]
	s_waitcnt vmcnt(20)
	v_mov_b32_e32 v50, v204
	v_mov_b32_e32 v51, v205
	v_mov_b32_e32 v52, v206
	v_mov_b32_e32 v53, v207
	v_lshlrev_b32_e32 v58, 16, v50
	v_and_b32_e32 v59, 0xffff0000, v50
	v_lshlrev_b32_e32 v50, 16, v51
	v_and_b32_e32 v51, 0xffff0000, v51
	v_lshlrev_b32_e32 v60, 16, v52
	v_and_b32_e32 v61, 0xffff0000, v52
	v_lshlrev_b32_e32 v52, 16, v53
	v_and_b32_e32 v53, 0xffff0000, v53
	v_pk_add_f32 v[50:51], v[46:47], v[50:51]
	v_pk_add_f32 v[58:59], v[44:45], v[58:59]
	v_pk_add_f32 v[52:53], v[42:43], v[52:53]
	v_pk_add_f32 v[60:61], v[40:41], v[60:61]
	v_cvt_pk_bf16_f32 v40, v58, v59
	v_cvt_pk_bf16_f32 v41, v50, v51
	v_mul_f32_e32 v51, v51, v51
	v_cvt_pk_bf16_f32 v42, v60, v61
	v_cvt_pk_bf16_f32 v43, v52, v53
	v_mul_f32_e32 v56, v59, v59
	v_mul_f32_e32 v57, v61, v61
	v_mul_f32_e32 v53, v53, v53
	v_fmac_f32_e32 v56, v58, v58
	v_fmac_f32_e32 v51, v50, v50
	v_fmac_f32_e32 v57, v60, v60
	v_fmac_f32_e32 v53, v52, v52
	v_add_f32_e32 v50, v56, v51
	v_add_f32_e32 v51, v57, v53
	v_add_f32_e32 v56, v50, v51
	s_waitcnt vmcnt(19)
	v_mov_b32_e32 v44, v208
	v_mov_b32_e32 v45, v209
	v_mov_b32_e32 v46, v210
	v_mov_b32_e32 v47, v211
	v_lshlrev_b32_e32 v50, 16, v44
	v_and_b32_e32 v51, 0xffff0000, v44
	v_lshlrev_b32_e32 v44, 16, v45
	v_and_b32_e32 v45, 0xffff0000, v45
	v_lshlrev_b32_e32 v52, 16, v46
	v_and_b32_e32 v53, 0xffff0000, v46
	v_lshlrev_b32_e32 v46, 16, v47
	v_and_b32_e32 v47, 0xffff0000, v47
	v_pk_add_f32 v[38:39], v[38:39], v[44:45]
	v_pk_add_f32 v[36:37], v[36:37], v[50:51]
	v_pk_add_f32 v[44:45], v[34:35], v[46:47]
	v_pk_add_f32 v[46:47], v[32:33], v[52:53]
	v_mul_f32_e32 v32, v37, v37
	v_mul_f32_e32 v33, v39, v39
	v_mul_f32_e32 v34, v47, v47
	v_mul_f32_e32 v35, v45, v45
	v_fmac_f32_e32 v32, v36, v36
	v_fmac_f32_e32 v33, v38, v38
	v_fmac_f32_e32 v34, v46, v46
	v_fmac_f32_e32 v35, v44, v44
	v_add_f32_e32 v32, v32, v33
	v_add_f32_e32 v33, v34, v35
	v_add_f32_e32 v32, v32, v33
	v_add_f32_e32 v32, v56, v32
	ds_bpermute_b32 v33, v120, v32
	v_lshl_add_u64 v[50:51], s[20:21], 0, v[54:55]
	global_store_dwordx4 v[50:51], v[40:43], off
	v_cvt_pk_bf16_f32 v34, v36, v37
	v_cvt_pk_bf16_f32 v35, v38, v39
	s_waitcnt lgkmcnt(0)
	v_add_f32_e32 v32, v32, v33
	ds_bpermute_b32 v33, v114, v32
	v_cvt_pk_bf16_f32 v36, v46, v47
	v_cvt_pk_bf16_f32 v37, v44, v45
	global_store_dwordx4 v[50:51], v[34:37], off offset:256
	s_and_saveexec_b64 s[0:1], vcc
	s_cbranch_execz .LBB0_819
	s_waitcnt lgkmcnt(0)
	v_add_f32_e32 v34, v32, v33
	v_lshlrev_b64 v[32:33], 7, v[48:49]
	v_lshl_add_u64 v[32:33], s[22:23], 0, v[32:33]
	v_lshl_add_u64 v[32:33], s[14:15], 2, v[32:33]
	s_lshl_b32 s16, s42, 2
	v_lshl_add_u64 v[32:33], v[32:33], 0, s[16:17]
	global_store_dword v[32:33], v34, off
; #define EPI_LOAD_X8(d0, d1, o) do { const u32x4 h_ = *(const u32x4*)(XBo + (o)); \
;         d0[0] = BFLO(h_.x); d0[1] = BFHI(h_.x); d0[2] = BFLO(h_.y); d0[3] = BFHI(h_.y); d1[0] = BFLO(h_.z); d1[1] = BFHI(h_.z); d1[2] = BFLO(h_.w); d1[3] = BFHI(h_.w); } while (0)
;     __device__ __forceinline__ void operator()(const f32x4 (&acc)[2][2][4][2], const Unit& u, int wr, int wc, int fr, int fq) const {
;     ...
;             for (int m = 0; m < 4; ++m) { const int r = row0 + ai * HALF + m * 16; const size_t off = (size_t)r * DM + col0; float ss = 0.f;
; #pragma unroll
;                 for (int bj = 0; bj < 2; ++bj) { const size_t o = off + bj * HALF;
;                     f32x4 v0, v1; if (F32BASE) { v0 = *(const f32x4*)(base + o); v1 = *(const f32x4*)(base + o + 4); } else EPI_LOAD_X8(v0, v1, o);
;                     v0 = v0 + acc[ai][bj][m][0]; v1 = v1 + acc[ai][bj][m][1]; EPI_STORE_X8(v0, v1, o); }
;                 ss += __shfl_xor(ss, 16); ss += __shfl_xor(ss, 32);
;                 if (fq == 0) SSQ[(size_t)r * NPART + u.pn * 4 + wc] = ss;
;                 if (m == 3) asm volatile("" ::: "memory"); }
.LBB0_819:
	s_or_b64 exec, exec, s[0:1]
	v_add_u32_e32 v32, 0xa0, v134
	s_waitcnt lgkmcnt(0)
	v_ashrrev_i32_e32 v33, 31, v32
	v_lshlrev_b64 v[34:35], 11, v[32:33]
	v_lshl_add_u64 v[34:35], v[34:35], 0, v[132:133]
	v_lshlrev_b64 v[38:39], 1, v[34:35]
	v_lshl_add_u64 v[40:41], s[18:19], 0, v[38:39]
	s_waitcnt vmcnt(21)
	v_mov_b32_e32 v34, v212
	v_mov_b32_e32 v35, v213
	v_mov_b32_e32 v36, v214
	v_mov_b32_e32 v37, v215
	v_lshlrev_b32_e32 v42, 16, v34
	v_and_b32_e32 v43, 0xffff0000, v34
	v_lshlrev_b32_e32 v34, 16, v35
	v_and_b32_e32 v35, 0xffff0000, v35
	v_lshlrev_b32_e32 v44, 16, v36
	v_and_b32_e32 v45, 0xffff0000, v36
	v_lshlrev_b32_e32 v36, 16, v37
	v_and_b32_e32 v37, 0xffff0000, v37
	v_pk_add_f32 v[34:35], v[30:31], v[34:35]
	v_pk_add_f32 v[42:43], v[28:29], v[42:43]
	v_pk_add_f32 v[36:37], v[26:27], v[36:37]
	v_pk_add_f32 v[44:45], v[24:25], v[44:45]
	v_cvt_pk_bf16_f32 v24, v42, v43
	v_cvt_pk_bf16_f32 v25, v34, v35
	v_mul_f32_e32 v35, v35, v35
	v_cvt_pk_bf16_f32 v26, v44, v45
	v_cvt_pk_bf16_f32 v27, v36, v37
	v_mul_f32_e32 v40, v43, v43
	v_mul_f32_e32 v41, v45, v45
	v_mul_f32_e32 v37, v37, v37
	v_fmac_f32_e32 v40, v42, v42
	v_fmac_f32_e32 v35, v34, v34
	v_fmac_f32_e32 v41, v44, v44
	v_fmac_f32_e32 v37, v36, v36
	v_add_f32_e32 v34, v40, v35
	v_add_f32_e32 v35, v41, v37
	v_add_f32_e32 v40, v34, v35
	s_waitcnt vmcnt(20)
	v_mov_b32_e32 v28, v216
	v_mov_b32_e32 v29, v217
	v_mov_b32_e32 v30, v218
	v_mov_b32_e32 v31, v219
	v_lshlrev_b32_e32 v34, 16, v28
	v_and_b32_e32 v35, 0xffff0000, v28
	v_lshlrev_b32_e32 v28, 16, v29
	v_and_b32_e32 v29, 0xffff0000, v29
	v_lshlrev_b32_e32 v36, 16, v30
	v_and_b32_e32 v37, 0xffff0000, v30
	v_lshlrev_b32_e32 v30, 16, v31
	v_and_b32_e32 v31, 0xffff0000, v31
	v_pk_add_f32 v[22:23], v[22:23], v[28:29]
	v_pk_add_f32 v[20:21], v[20:21], v[34:35]
	v_pk_add_f32 v[28:29], v[18:19], v[30:31]
	v_pk_add_f32 v[30:31], v[16:17], v[36:37]
	v_mul_f32_e32 v16, v21, v21
	v_mul_f32_e32 v17, v23, v23
	v_mul_f32_e32 v18, v31, v31
	v_mul_f32_e32 v19, v29, v29
	v_fmac_f32_e32 v16, v20, v20
	v_fmac_f32_e32 v17, v22, v22
	v_fmac_f32_e32 v18, v30, v30
	v_fmac_f32_e32 v19, v28, v28
	v_add_f32_e32 v16, v16, v17
	v_add_f32_e32 v17, v18, v19
	v_add_f32_e32 v16, v16, v17
	v_add_f32_e32 v16, v40, v16
	ds_bpermute_b32 v17, v120, v16
	v_lshl_add_u64 v[34:35], s[20:21], 0, v[38:39]
	global_store_dwordx4 v[34:35], v[24:27], off
	v_cvt_pk_bf16_f32 v18, v20, v21
	v_cvt_pk_bf16_f32 v19, v22, v23
	s_waitcnt lgkmcnt(0)
	v_add_f32_e32 v16, v16, v17
	ds_bpermute_b32 v17, v114, v16
	v_cvt_pk_bf16_f32 v20, v30, v31
	v_cvt_pk_bf16_f32 v21, v28, v29
	global_store_dwordx4 v[34:35], v[18:21], off offset:256
	s_and_saveexec_b64 s[0:1], vcc
	s_cbranch_execz .LBB0_821
	s_waitcnt lgkmcnt(0)
	v_add_f32_e32 v18, v16, v17
	v_lshlrev_b64 v[16:17], 7, v[32:33]
	v_lshl_add_u64 v[16:17], s[22:23], 0, v[16:17]
	v_lshl_add_u64 v[16:17], s[14:15], 2, v[16:17]
	s_lshl_b32 s16, s42, 2
	v_lshl_add_u64 v[16:17], v[16:17], 0, s[16:17]
	global_store_dword v[16:17], v18, off
.LBB0_821:
	s_or_b64 exec, exec, s[0:1]
	v_add_u32_e32 v16, 0xb0, v134
	s_waitcnt lgkmcnt(0)
	v_ashrrev_i32_e32 v17, 31, v16
	v_lshlrev_b64 v[18:19], 11, v[16:17]
	v_lshl_add_u64 v[18:19], v[18:19], 0, v[132:133]
	v_lshlrev_b64 v[22:23], 1, v[18:19]
	v_lshl_add_u64 v[24:25], s[18:19], 0, v[22:23]
	s_waitcnt vmcnt(22)
	v_mov_b32_e32 v18, v220
	v_mov_b32_e32 v19, v221
	v_mov_b32_e32 v20, v222
	v_mov_b32_e32 v21, v223
	v_lshlrev_b32_e32 v26, 16, v18
	v_and_b32_e32 v27, 0xffff0000, v18
	v_lshlrev_b32_e32 v18, 16, v19
	v_and_b32_e32 v19, 0xffff0000, v19
	v_lshlrev_b32_e32 v28, 16, v20
	v_and_b32_e32 v29, 0xffff0000, v20
	v_lshlrev_b32_e32 v20, 16, v21
	v_and_b32_e32 v21, 0xffff0000, v21
	v_pk_add_f32 v[18:19], v[14:15], v[18:19]
	v_pk_add_f32 v[26:27], v[12:13], v[26:27]
	v_pk_add_f32 v[20:21], v[10:11], v[20:21]
	v_pk_add_f32 v[28:29], v[8:9], v[28:29]
	v_cvt_pk_bf16_f32 v8, v26, v27
	v_cvt_pk_bf16_f32 v9, v18, v19
	v_mul_f32_e32 v19, v19, v19
	v_cvt_pk_bf16_f32 v10, v28, v29
	v_cvt_pk_bf16_f32 v11, v20, v21
	v_mul_f32_e32 v24, v27, v27
	v_mul_f32_e32 v25, v29, v29
	v_mul_f32_e32 v21, v21, v21
	v_fmac_f32_e32 v24, v26, v26
	v_fmac_f32_e32 v19, v18, v18
	v_fmac_f32_e32 v25, v28, v28
	v_fmac_f32_e32 v21, v20, v20
	v_add_f32_e32 v18, v24, v19
	v_add_f32_e32 v19, v25, v21
	v_add_f32_e32 v24, v18, v19
	s_waitcnt vmcnt(21)
	v_mov_b32_e32 v12, v224
	v_mov_b32_e32 v13, v225
	v_mov_b32_e32 v14, v226
	v_mov_b32_e32 v15, v227
	v_lshlrev_b32_e32 v18, 16, v12
	v_and_b32_e32 v19, 0xffff0000, v12
	v_lshlrev_b32_e32 v12, 16, v13
	v_and_b32_e32 v13, 0xffff0000, v13
	v_lshlrev_b32_e32 v20, 16, v14
	v_and_b32_e32 v21, 0xffff0000, v14
	v_lshlrev_b32_e32 v14, 16, v15
	v_and_b32_e32 v15, 0xffff0000, v15
	v_pk_add_f32 v[6:7], v[6:7], v[12:13]
	v_pk_add_f32 v[4:5], v[4:5], v[18:19]
	v_pk_add_f32 v[12:13], v[2:3], v[14:15]
	v_pk_add_f32 v[14:15], v[0:1], v[20:21]
	v_mul_f32_e32 v0, v5, v5
	v_mul_f32_e32 v1, v7, v7
	v_mul_f32_e32 v2, v15, v15
	v_mul_f32_e32 v3, v13, v13
	v_fmac_f32_e32 v0, v4, v4
	v_fmac_f32_e32 v1, v6, v6
	v_fmac_f32_e32 v2, v14, v14
	v_fmac_f32_e32 v3, v12, v12
	v_add_f32_e32 v0, v0, v1
	v_add_f32_e32 v1, v2, v3
	v_add_f32_e32 v0, v0, v1
	v_add_f32_e32 v0, v24, v0
	ds_bpermute_b32 v1, v120, v0
	v_lshl_add_u64 v[18:19], s[20:21], 0, v[22:23]
	global_store_dwordx4 v[18:19], v[8:11], off
	v_cvt_pk_bf16_f32 v2, v4, v5
	v_cvt_pk_bf16_f32 v3, v6, v7
	s_waitcnt lgkmcnt(0)
	v_add_f32_e32 v0, v0, v1
	ds_bpermute_b32 v1, v114, v0
	v_cvt_pk_bf16_f32 v4, v14, v15
	v_cvt_pk_bf16_f32 v5, v12, v13
	global_store_dwordx4 v[18:19], v[2:5], off offset:256
	s_and_saveexec_b64 s[0:1], vcc
	s_cbranch_execz .LBB0_823
	s_waitcnt lgkmcnt(0)
	v_add_f32_e32 v2, v0, v1
	v_lshlrev_b64 v[0:1], 7, v[16:17]
	v_lshl_add_u64 v[0:1], s[22:23], 0, v[0:1]
	v_lshl_add_u64 v[0:1], s[14:15], 2, v[0:1]
	s_lshl_b32 s16, s42, 2
	v_lshl_add_u64 v[0:1], v[0:1], 0, s[16:17]
	global_store_dword v[0:1], v2, off

; #define EPI_LOAD_X8(d0, d1, o) do { const u32x4 h_ = *(const u32x4*)(XBo + (o)); \
;         d0[0] = BFLO(h_.x); d0[1] = BFHI(h_.x); d0[2] = BFLO(h_.y); d0[3] = BFHI(h_.y); d1[0] = BFLO(h_.z); d1[1] = BFHI(h_.z); d1[2] = BFLO(h_.w); d1[3] = BFHI(h_.w); } while (0)
;     __device__ __forceinline__ void operator()(const f32x4 (&acc)[2][2][4][2], const Unit& u, int wr, int wc, int fr, int fq) const {
;         const int row0 = u.pm * BM + wr * 64 + fr, col0 = u.pn * BM + wc * 32 + 8 * fq;
; #pragma unroll
;         for (int ai = 0; ai < 2; ++ai)
; #pragma unroll
;             for (int m = 0; m < 4; ++m) { const int r = row0 + ai * HALF + m * 16; const size_t off = (size_t)r * DM + col0; float ss = 0.f;
; #pragma unroll
;                 for (int bj = 0; bj < 2; ++bj) { const size_t o = off + bj * HALF;
;                     f32x4 v0, v1; if (F32BASE) { v0 = *(const f32x4*)(base + o); v1 = *(const f32x4*)(base + o + 4); } else EPI_LOAD_X8(v0, v1, o);
;                     v0 = v0 + acc[ai][bj][m][0]; v1 = v1 + acc[ai][bj][m][1]; EPI_STORE_X8(v0, v1, o); }
;                 ss += __shfl_xor(ss, 16); ss += __shfl_xor(ss, 32);
;                 if (fq == 0) SSQ[(size_t)r * NPART + u.pn * 4 + wc] = ss;
.LBB0_2383:
	s_lshl_b32 s0, s54, 8
	s_add_i32 s0, s0, s43
	v_mbcnt_lo_u32_b32 v160, -1, 0
	v_mbcnt_hi_u32_b32 v160, -1, v160
	v_xor_b32_e32 v161, 32, v145
	v_and_or_b32 v134, v160, 15, s0
	s_lshl_b32 s0, s53, 8
	v_ashrrev_i32_e32 v132, 1, v160
	s_or_b32 s0, s0, s44
	v_and_b32_e32 v132, -8, v132
	v_add_u32_e32 v132, s0, v132
	v_ashrrev_i32_e32 v135, 31, v134
	v_ashrrev_i32_e32 v133, 31, v132
	v_lshlrev_b64 v[146:147], 11, v[134:135]
	v_lshl_add_u64 v[146:147], v[146:147], 0, v[132:133]
	v_lshlrev_b64 v[150:151], 1, v[146:147]
	v_lshl_add_u64 v[152:153], s[18:19], 0, v[150:151]
	global_load_dwordx4 v[164:167], v150, s[18:19]
	global_load_dwordx4 v[168:171], v150, s[18:19] offset:256
	s_add_u32 vcc_lo, s18, 0x10000
	s_addc_u32 vcc_hi, s19, 0
	global_load_dwordx4 v[172:175], v150, vcc
	global_load_dwordx4 v[176:179], v150, vcc offset:256
	s_add_u32 s0, s18, 0x20000
	s_addc_u32 s1, s19, 0
	global_load_dwordx4 v[180:183], v150, s[0:1]
	global_load_dwordx4 v[184:187], v150, s[0:1] offset:256
	s_add_u32 vcc_lo, s18, 0x30000
	s_addc_u32 vcc_hi, s19, 0
	global_load_dwordx4 v[188:191], v150, vcc
	global_load_dwordx4 v[192:195], v150, vcc offset:256
	s_add_u32 s0, s18, 0x80000
	s_addc_u32 s1, s19, 0
	global_load_dwordx4 v[196:199], v150, s[0:1]
	global_load_dwordx4 v[200:203], v150, s[0:1] offset:256
	s_add_u32 vcc_lo, s18, 0x90000
	s_addc_u32 vcc_hi, s19, 0
	global_load_dwordx4 v[204:207], v150, vcc
	global_load_dwordx4 v[208:211], v150, vcc offset:256
	s_add_u32 s0, s18, 0xa0000
	s_addc_u32 s1, s19, 0
	global_load_dwordx4 v[212:215], v150, s[0:1]
	global_load_dwordx4 v[216:219], v150, s[0:1] offset:256
	s_add_u32 vcc_lo, s18, 0xb0000
	s_addc_u32 vcc_hi, s19, 0
	global_load_dwordx4 v[220:223], v150, vcc
	global_load_dwordx4 v[224:227], v150, vcc offset:256
	s_lshl_b32 s14, s53, 2
	v_cmp_gt_u32_e32 vcc, 16, v160
	s_ashr_i32 s15, s14, 31
	s_waitcnt vmcnt(15)
	v_mov_b32_e32 v146, v164
	v_mov_b32_e32 v147, v165
	v_mov_b32_e32 v148, v166
	v_mov_b32_e32 v149, v167
	v_lshlrev_b32_e32 v154, 16, v146
	v_and_b32_e32 v155, 0xffff0000, v146
	v_lshlrev_b32_e32 v146, 16, v147
	v_and_b32_e32 v147, 0xffff0000, v147
	v_lshlrev_b32_e32 v156, 16, v148
	v_and_b32_e32 v157, 0xffff0000, v148
	v_lshlrev_b32_e32 v148, 16, v149
	v_and_b32_e32 v149, 0xffff0000, v149
	v_pk_add_f32 v[126:127], v[126:127], v[146:147]
	v_pk_add_f32 v[154:155], v[124:125], v[154:155]
	v_pk_add_f32 v[158:159], v[122:123], v[148:149]
	v_pk_add_f32 v[156:157], v[120:121], v[156:157]
	v_cvt_pk_bf16_f32 v122, v154, v155
	v_cvt_pk_bf16_f32 v123, v126, v127
	v_mul_f32_e32 v127, v127, v127
	v_cvt_pk_bf16_f32 v124, v156, v157
	v_cvt_pk_bf16_f32 v125, v158, v159
	v_mul_f32_e32 v152, v155, v155
	v_mul_f32_e32 v153, v157, v157
	v_mul_f32_e32 v155, v159, v159
	v_fmac_f32_e32 v152, v154, v154
	v_fmac_f32_e32 v127, v126, v126
	v_fmac_f32_e32 v153, v156, v156
	v_fmac_f32_e32 v155, v158, v158
	v_add_f32_e32 v126, v152, v127
	v_add_f32_e32 v127, v153, v155
	v_add_f32_e32 v154, v126, v127
	v_and_b32_e32 v121, 64, v145
	v_xor_b32_e32 v120, 16, v145
	v_add_u32_e32 v121, 64, v121
	v_cmp_lt_i32_e64 s[0:1], v120, v121
	s_waitcnt vmcnt(14)
	v_mov_b32_e32 v146, v168
	v_mov_b32_e32 v147, v169
	v_mov_b32_e32 v148, v170
	v_mov_b32_e32 v149, v171
	v_lshlrev_b32_e32 v126, 16, v146
	v_and_b32_e32 v127, 0xffff0000, v146
	v_lshlrev_b32_e32 v146, 16, v147
	v_and_b32_e32 v147, 0xffff0000, v147
	v_lshlrev_b32_e32 v152, 16, v148
	v_and_b32_e32 v153, 0xffff0000, v148
	v_lshlrev_b32_e32 v148, 16, v149
	v_and_b32_e32 v149, 0xffff0000, v149
	v_pk_add_f32 v[118:119], v[118:119], v[146:147]
	v_pk_add_f32 v[116:117], v[116:117], v[126:127]
	v_pk_add_f32 v[126:127], v[114:115], v[148:149]
	v_pk_add_f32 v[146:147], v[112:113], v[152:153]
	v_mul_f32_e32 v112, v117, v117
	v_mul_f32_e32 v113, v119, v119
	v_mul_f32_e32 v114, v147, v147
	v_mul_f32_e32 v115, v127, v127
	v_fmac_f32_e32 v112, v116, v116
	v_fmac_f32_e32 v113, v118, v118
	v_fmac_f32_e32 v114, v146, v146
	v_fmac_f32_e32 v115, v126, v126
	v_add_f32_e32 v112, v112, v113
	v_add_f32_e32 v113, v114, v115
	v_cndmask_b32_e64 v120, v145, v120, s[0:1]
	v_add_f32_e32 v112, v112, v113
	v_lshlrev_b32_e32 v120, 2, v120
	v_add_f32_e32 v112, v154, v112
	ds_bpermute_b32 v113, v120, v112
	v_cmp_lt_i32_e64 s[0:1], v161, v121
	v_lshl_add_u64 v[148:149], s[20:21], 0, v[150:151]
	global_store_dwordx4 v[148:149], v[122:125], off
	v_cndmask_b32_e64 v114, v145, v161, s[0:1]
	s_waitcnt lgkmcnt(0)
	v_add_f32_e32 v112, v112, v113
	v_lshlrev_b32_e32 v114, 2, v114
	ds_bpermute_b32 v113, v114, v112
	v_cvt_pk_bf16_f32 v116, v116, v117
	v_cvt_pk_bf16_f32 v117, v118, v119
	v_cvt_pk_bf16_f32 v118, v146, v147
	v_cvt_pk_bf16_f32 v119, v126, v127
	global_store_dwordx4 v[148:149], v[116:119], off offset:256
	s_and_saveexec_b64 s[0:1], vcc
	s_cbranch_execz .LBB0_2385
	s_waitcnt lgkmcnt(0)
	v_add_f32_e32 v115, v112, v113
	v_lshlrev_b64 v[112:113], 7, v[134:135]
	v_lshl_add_u64 v[112:113], s[22:23], 0, v[112:113]
	v_lshl_add_u64 v[112:113], s[14:15], 2, v[112:113]
	s_lshl_b32 s16, s42, 2
	v_lshl_add_u64 v[112:113], v[112:113], 0, s[16:17]
	global_store_dword v[112:113], v115, off
